# v62 + LDS-DMA loads converted to saddr+voffset form in the 6 GEMM K-loops (removes 16 v_lshl_add_u64 per iteration; inst offset compensated in m0)
# speedup vs baseline: 1.0172x; 1.0066x over previous
.LBB0_173:
	ds_read_b128 v[144:147], v155
	ds_read_b128 v[148:151], v155 offset:1024
	ds_read_b128 v[158:161], v155 offset:2048
	ds_read_b128 v[162:165], v155 offset:3072
	ds_read_b128 v[166:169], v156
	ds_read_b128 v[170:173], v156 offset:1024
	ds_read_b128 v[174:177], v156 offset:2048
	ds_read_b128 v[178:181], v156 offset:3072
	s_add_u32 s68, s66, 0xfff80080
	s_addc_u32 s69, s67, -1
	s_cmp_eq_u32 s77, 28
	s_cselect_b32 s71, s55, s69
	s_cselect_b32 s70, s59, s68
	s_cselect_b32 s69, s57, s76
	s_cselect_b32 s68, s65, s73
	s_add_i32 m0, s25, 0xc000
	ds_read_b128 v[182:185], v157
	ds_read_b128 v[186:189], v157 offset:1024
	ds_read_b128 v[190:193], v157 offset:2048
	ds_read_b128 v[194:197], v157 offset:3072
	ds_read_b128 v[198:201], v157 offset:4096
	ds_read_b128 v[202:205], v157 offset:5120
	ds_read_b128 v[206:209], v157 offset:6144
	ds_read_b128 v[210:213], v157 offset:7168
	global_load_lds_dwordx4 v136, s[66:67]
	s_add_i32 m0, s25, 0xe000
	s_nop 0
	global_load_lds_dwordx4 v138, s[66:67]
	s_waitcnt vmcnt(8)
	s_waitcnt lgkmcnt(0)
	s_setprio 1
	s_barrier
	v_mfma_i32_16x16x64_i8 v[124:127], v[144:147], v[182:185], v[124:127]
	v_mfma_i32_16x16x64_i8 v[116:119], v[158:161], v[182:185], v[116:119]
	v_mfma_i32_16x16x64_i8 v[108:111], v[144:147], v[190:193], v[108:111]
	v_mfma_i32_16x16x64_i8 v[100:103], v[158:161], v[190:193], v[100:103]
	v_mfma_i32_16x16x64_i8 v[92:95], v[144:147], v[198:201], v[92:95]
	v_mfma_i32_16x16x64_i8 v[84:87], v[158:161], v[198:201], v[84:87]
	v_mfma_i32_16x16x64_i8 v[76:79], v[144:147], v[206:209], v[76:79]
	v_mfma_i32_16x16x64_i8 v[68:71], v[158:161], v[206:209], v[68:71]
	v_mfma_i32_16x16x64_i8 v[124:127], v[148:151], v[186:189], v[124:127]
	v_mfma_i32_16x16x64_i8 v[116:119], v[162:165], v[186:189], v[116:119]
	v_mfma_i32_16x16x64_i8 v[108:111], v[148:151], v[194:197], v[108:111]
	v_mfma_i32_16x16x64_i8 v[100:103], v[162:165], v[194:197], v[100:103]
	v_mfma_i32_16x16x64_i8 v[92:95], v[148:151], v[202:205], v[92:95]
	v_mfma_i32_16x16x64_i8 v[84:87], v[162:165], v[202:205], v[84:87]
	v_mfma_i32_16x16x64_i8 v[76:79], v[148:151], v[210:213], v[76:79]
	v_mfma_i32_16x16x64_i8 v[68:71], v[162:165], v[210:213], v[68:71]
	v_mfma_i32_16x16x64_i8 v[120:123], v[166:169], v[182:185], v[120:123]
	v_mfma_i32_16x16x64_i8 v[112:115], v[174:177], v[182:185], v[112:115]
	v_mfma_i32_16x16x64_i8 v[104:107], v[166:169], v[190:193], v[104:107]
	v_mfma_i32_16x16x64_i8 v[96:99], v[174:177], v[190:193], v[96:99]
	v_mfma_i32_16x16x64_i8 v[88:91], v[166:169], v[198:201], v[88:91]
	v_mfma_i32_16x16x64_i8 v[80:83], v[174:177], v[198:201], v[80:83]
	v_mfma_i32_16x16x64_i8 v[72:75], v[166:169], v[206:209], v[72:75]
	v_mfma_i32_16x16x64_i8 v[64:67], v[174:177], v[206:209], v[64:67]
	v_mfma_i32_16x16x64_i8 v[120:123], v[170:173], v[186:189], v[120:123]
	v_mfma_i32_16x16x64_i8 v[112:115], v[178:181], v[186:189], v[112:115]
	v_mfma_i32_16x16x64_i8 v[104:107], v[170:173], v[194:197], v[104:107]
	v_mfma_i32_16x16x64_i8 v[96:99], v[178:181], v[194:197], v[96:99]
	v_mfma_i32_16x16x64_i8 v[88:91], v[170:173], v[202:205], v[88:91]
	v_mfma_i32_16x16x64_i8 v[80:83], v[178:181], v[202:205], v[80:83]
	v_mfma_i32_16x16x64_i8 v[72:75], v[170:173], v[210:213], v[72:75]
	v_mfma_i32_16x16x64_i8 v[64:67], v[178:181], v[210:213], v[64:67]
	s_barrier
	s_setprio 0
	s_add_i32 s78, s35, s13
	s_mov_b32 m0, s78
	ds_read_b128 v[182:185], v157 offset:16384
	ds_read_b128 v[186:189], v157 offset:17408
	ds_read_b128 v[190:193], v157 offset:18432
	ds_read_b128 v[194:197], v157 offset:19456
	ds_read_b128 v[198:201], v157 offset:20480
	ds_read_b128 v[202:205], v157 offset:21504
	ds_read_b128 v[206:209], v157 offset:22528
	ds_read_b128 v[210:213], v157 offset:23552
	global_load_lds_dwordx4 v132, s[68:69]
	s_add_i32 m0, s78, 0x2000
	s_add_u32 s78, s68, 0x80000
	s_mov_b64 s[98:99], s[68:69]
	s_addc_u32 s79, s69, 0
	s_add_i32 s81, s52, s13
	global_load_lds_dwordx4 v128, s[98:99]
	s_mov_b32 m0, s81
	s_mov_b64 s[100:101], s[70:71]
	global_load_lds_dwordx4 v132, s[78:79]
	s_add_i32 m0, s81, 0x2000
	s_nop 0
	global_load_lds_dwordx4 v128, s[78:79]
	s_mov_b64 s[100:101], s[70:71]
	s_mov_b32 m0, s25
	s_nop 0
	global_load_lds_dwordx4 v134, s[100:101]
	s_mov_b32 m0, s26
	s_nop 0
	global_load_lds_dwordx4 v130, s[100:101]
	s_waitcnt vmcnt(8)
	s_waitcnt lgkmcnt(0)
	s_setprio 1
	s_barrier
	v_mfma_i32_16x16x64_i8 v[60:63], v[144:147], v[182:185], v[60:63]
	v_mfma_i32_16x16x64_i8 v[52:55], v[158:161], v[182:185], v[52:55]
	v_mfma_i32_16x16x64_i8 v[44:47], v[144:147], v[190:193], v[44:47]
	v_mfma_i32_16x16x64_i8 v[36:39], v[158:161], v[190:193], v[36:39]
	v_mfma_i32_16x16x64_i8 v[28:31], v[144:147], v[198:201], v[28:31]
	v_mfma_i32_16x16x64_i8 v[20:23], v[158:161], v[198:201], v[20:23]
	v_mfma_i32_16x16x64_i8 v[12:15], v[144:147], v[206:209], v[12:15]
	v_mfma_i32_16x16x64_i8 v[4:7], v[158:161], v[206:209], v[4:7]
	v_mfma_i32_16x16x64_i8 v[60:63], v[148:151], v[186:189], v[60:63]
	v_mfma_i32_16x16x64_i8 v[52:55], v[162:165], v[186:189], v[52:55]
	v_mfma_i32_16x16x64_i8 v[44:47], v[148:151], v[194:197], v[44:47]
	v_mfma_i32_16x16x64_i8 v[36:39], v[162:165], v[194:197], v[36:39]
	v_mfma_i32_16x16x64_i8 v[28:31], v[148:151], v[202:205], v[28:31]
	v_mfma_i32_16x16x64_i8 v[20:23], v[162:165], v[202:205], v[20:23]
	v_mfma_i32_16x16x64_i8 v[12:15], v[148:151], v[210:213], v[12:15]
	v_mfma_i32_16x16x64_i8 v[4:7], v[162:165], v[210:213], v[4:7]
	v_mfma_i32_16x16x64_i8 v[56:59], v[166:169], v[182:185], v[56:59]
	v_mfma_i32_16x16x64_i8 v[48:51], v[174:177], v[182:185], v[48:51]
	v_mfma_i32_16x16x64_i8 v[40:43], v[166:169], v[190:193], v[40:43]
	v_mfma_i32_16x16x64_i8 v[32:35], v[174:177], v[190:193], v[32:35]
	v_mfma_i32_16x16x64_i8 v[24:27], v[166:169], v[198:201], v[24:27]
	v_mfma_i32_16x16x64_i8 v[16:19], v[174:177], v[198:201], v[16:19]
	v_mfma_i32_16x16x64_i8 v[8:11], v[166:169], v[206:209], v[8:11]
	v_mfma_i32_16x16x64_i8 v[0:3], v[174:177], v[206:209], v[0:3]
	v_mfma_i32_16x16x64_i8 v[56:59], v[170:173], v[186:189], v[56:59]
	v_mfma_i32_16x16x64_i8 v[48:51], v[178:181], v[186:189], v[48:51]
	v_mfma_i32_16x16x64_i8 v[40:43], v[170:173], v[194:197], v[40:43]
	v_mfma_i32_16x16x64_i8 v[32:35], v[178:181], v[194:197], v[32:35]
	v_mfma_i32_16x16x64_i8 v[24:27], v[170:173], v[202:205], v[24:27]
	v_mfma_i32_16x16x64_i8 v[16:19], v[178:181], v[202:205], v[16:19]
	v_mfma_i32_16x16x64_i8 v[8:11], v[170:173], v[210:213], v[8:11]
	v_mfma_i32_16x16x64_i8 v[0:3], v[178:181], v[210:213], v[0:3]
	s_barrier
	s_setprio 0
	s_add_i32 s78, 0, 0x18000
	s_add_i32 s79, 0, 0x1c000
	v_add_u32_e32 v162, s78, v153
	v_add_u32_e32 v178, s79, v153
	ds_read_b128 v[144:147], v162
	ds_read_b128 v[148:151], v162 offset:1024
	ds_read_b128 v[158:161], v162 offset:2048
	ds_read_b128 v[162:165], v162 offset:3072
	ds_read_b128 v[166:169], v178
	ds_read_b128 v[170:173], v178 offset:1024
	ds_read_b128 v[174:177], v178 offset:2048
	ds_read_b128 v[178:181], v178 offset:3072
	s_add_u32 s70, s70, 0x80000
	s_addc_u32 s71, s71, 0
	s_mov_b32 m0, s27
	ds_read_b128 v[182:185], v157 offset:32768
	ds_read_b128 v[186:189], v157 offset:33792
	ds_read_b128 v[190:193], v157 offset:34816
	ds_read_b128 v[194:197], v157 offset:35840
	ds_read_b128 v[198:201], v157 offset:36864
	ds_read_b128 v[202:205], v157 offset:37888
	ds_read_b128 v[206:209], v157 offset:38912
	ds_read_b128 v[210:213], v157 offset:39936
	global_load_lds_dwordx4 v134, s[70:71]
	s_mov_b32 m0, s28
	s_nop 0
	global_load_lds_dwordx4 v130, s[70:71]
	s_waitcnt vmcnt(8)
	s_waitcnt lgkmcnt(0)
	s_setprio 1
	s_barrier
	v_mfma_i32_16x16x64_i8 v[124:127], v[144:147], v[182:185], v[124:127]
	v_mfma_i32_16x16x64_i8 v[116:119], v[158:161], v[182:185], v[116:119]
	v_mfma_i32_16x16x64_i8 v[108:111], v[144:147], v[190:193], v[108:111]
	v_mfma_i32_16x16x64_i8 v[100:103], v[158:161], v[190:193], v[100:103]
	v_mfma_i32_16x16x64_i8 v[92:95], v[144:147], v[198:201], v[92:95]
	v_mfma_i32_16x16x64_i8 v[84:87], v[158:161], v[198:201], v[84:87]
	v_mfma_i32_16x16x64_i8 v[76:79], v[144:147], v[206:209], v[76:79]
	v_mfma_i32_16x16x64_i8 v[68:71], v[158:161], v[206:209], v[68:71]
	v_mfma_i32_16x16x64_i8 v[124:127], v[148:151], v[186:189], v[124:127]
	v_mfma_i32_16x16x64_i8 v[116:119], v[162:165], v[186:189], v[116:119]
	v_mfma_i32_16x16x64_i8 v[108:111], v[148:151], v[194:197], v[108:111]
	v_mfma_i32_16x16x64_i8 v[100:103], v[162:165], v[194:197], v[100:103]
	v_mfma_i32_16x16x64_i8 v[92:95], v[148:151], v[202:205], v[92:95]
	v_mfma_i32_16x16x64_i8 v[84:87], v[162:165], v[202:205], v[84:87]
	v_mfma_i32_16x16x64_i8 v[76:79], v[148:151], v[210:213], v[76:79]
	v_mfma_i32_16x16x64_i8 v[68:71], v[162:165], v[210:213], v[68:71]
	v_mfma_i32_16x16x64_i8 v[120:123], v[166:169], v[182:185], v[120:123]
	v_mfma_i32_16x16x64_i8 v[112:115], v[174:177], v[182:185], v[112:115]
	v_mfma_i32_16x16x64_i8 v[104:107], v[166:169], v[190:193], v[104:107]
	v_mfma_i32_16x16x64_i8 v[96:99], v[174:177], v[190:193], v[96:99]
	v_mfma_i32_16x16x64_i8 v[88:91], v[166:169], v[198:201], v[88:91]
	v_mfma_i32_16x16x64_i8 v[80:83], v[174:177], v[198:201], v[80:83]
	v_mfma_i32_16x16x64_i8 v[72:75], v[166:169], v[206:209], v[72:75]
	v_mfma_i32_16x16x64_i8 v[64:67], v[174:177], v[206:209], v[64:67]
	v_mfma_i32_16x16x64_i8 v[120:123], v[170:173], v[186:189], v[120:123]
	v_mfma_i32_16x16x64_i8 v[112:115], v[178:181], v[186:189], v[112:115]
	v_mfma_i32_16x16x64_i8 v[104:107], v[170:173], v[194:197], v[104:107]
	v_mfma_i32_16x16x64_i8 v[96:99], v[178:181], v[194:197], v[96:99]
	v_mfma_i32_16x16x64_i8 v[88:91], v[170:173], v[202:205], v[88:91]
	v_mfma_i32_16x16x64_i8 v[80:83], v[178:181], v[202:205], v[80:83]
	v_mfma_i32_16x16x64_i8 v[72:75], v[170:173], v[210:213], v[72:75]
	v_mfma_i32_16x16x64_i8 v[64:67], v[178:181], v[210:213], v[64:67]
	s_barrier
	s_setprio 0
	s_add_i32 s70, s78, s13
	s_add_i32 m0, s70, -128
	ds_read_b128 v[182:185], v157 offset:49152
	ds_read_b128 v[186:189], v157 offset:50176
	ds_read_b128 v[190:193], v157 offset:51200
	ds_read_b128 v[194:197], v157 offset:52224
	ds_read_b128 v[198:201], v157 offset:53248
	ds_read_b128 v[202:205], v157 offset:54272
	ds_read_b128 v[206:209], v157 offset:55296
	ds_read_b128 v[210:213], v157 offset:56320
	global_load_lds_dwordx4 v132, s[68:69] offset:128
	s_add_i32 m0, s70, 8064
	s_add_u32 s68, s68, 0x80080
	s_addc_u32 s69, s69, 0
	s_add_i32 s70, s79, s13
	global_load_lds_dwordx4 v128, s[98:99] offset:128
	s_mov_b32 m0, s70
	s_nop 0
	global_load_lds_dwordx4 v132, s[68:69]
	s_add_i32 m0, s70, 0x2000
	s_nop 0
	global_load_lds_dwordx4 v128, s[68:69]
	s_add_i32 m0, s31, -128
	s_nop 0
	global_load_lds_dwordx4 v134, s[100:101] offset:128
	s_add_i32 m0, s33, -128
	s_nop 0
	global_load_lds_dwordx4 v130, s[100:101] offset:128
	s_waitcnt vmcnt(8)
	s_waitcnt lgkmcnt(0)
	s_setprio 1
	s_barrier
	v_mfma_i32_16x16x64_i8 v[60:63], v[144:147], v[182:185], v[60:63]
	v_mfma_i32_16x16x64_i8 v[52:55], v[158:161], v[182:185], v[52:55]
	v_mfma_i32_16x16x64_i8 v[44:47], v[144:147], v[190:193], v[44:47]
	v_mfma_i32_16x16x64_i8 v[36:39], v[158:161], v[190:193], v[36:39]
	v_mfma_i32_16x16x64_i8 v[28:31], v[144:147], v[198:201], v[28:31]
	v_mfma_i32_16x16x64_i8 v[20:23], v[158:161], v[198:201], v[20:23]
	v_mfma_i32_16x16x64_i8 v[12:15], v[144:147], v[206:209], v[12:15]
	v_mfma_i32_16x16x64_i8 v[4:7], v[158:161], v[206:209], v[4:7]
	v_mfma_i32_16x16x64_i8 v[60:63], v[148:151], v[186:189], v[60:63]
	v_mfma_i32_16x16x64_i8 v[52:55], v[162:165], v[186:189], v[52:55]
	v_mfma_i32_16x16x64_i8 v[44:47], v[148:151], v[194:197], v[44:47]
	v_mfma_i32_16x16x64_i8 v[36:39], v[162:165], v[194:197], v[36:39]
	v_mfma_i32_16x16x64_i8 v[28:31], v[148:151], v[202:205], v[28:31]
	v_mfma_i32_16x16x64_i8 v[20:23], v[162:165], v[202:205], v[20:23]
	v_mfma_i32_16x16x64_i8 v[12:15], v[148:151], v[210:213], v[12:15]
	v_mfma_i32_16x16x64_i8 v[4:7], v[162:165], v[210:213], v[4:7]
	v_mfma_i32_16x16x64_i8 v[56:59], v[166:169], v[182:185], v[56:59]
	v_mfma_i32_16x16x64_i8 v[48:51], v[174:177], v[182:185], v[48:51]
	v_mfma_i32_16x16x64_i8 v[40:43], v[166:169], v[190:193], v[40:43]
	v_mfma_i32_16x16x64_i8 v[32:35], v[174:177], v[190:193], v[32:35]
	v_mfma_i32_16x16x64_i8 v[24:27], v[166:169], v[198:201], v[24:27]
	v_mfma_i32_16x16x64_i8 v[16:19], v[174:177], v[198:201], v[16:19]
	v_mfma_i32_16x16x64_i8 v[8:11], v[166:169], v[206:209], v[8:11]
	v_mfma_i32_16x16x64_i8 v[0:3], v[174:177], v[206:209], v[0:3]
	v_mfma_i32_16x16x64_i8 v[56:59], v[170:173], v[186:189], v[56:59]
	v_mfma_i32_16x16x64_i8 v[48:51], v[178:181], v[186:189], v[48:51]
	v_mfma_i32_16x16x64_i8 v[40:43], v[170:173], v[194:197], v[40:43]
	v_mfma_i32_16x16x64_i8 v[32:35], v[178:181], v[194:197], v[32:35]
	v_mfma_i32_16x16x64_i8 v[24:27], v[170:173], v[202:205], v[24:27]
	v_mfma_i32_16x16x64_i8 v[16:19], v[178:181], v[202:205], v[16:19]
	v_mfma_i32_16x16x64_i8 v[8:11], v[170:173], v[210:213], v[8:11]
	v_mfma_i32_16x16x64_i8 v[0:3], v[178:181], v[210:213], v[0:3]
	s_barrier
	s_setprio 0
	s_add_i32 s77, s77, 2
	s_add_u32 s66, s66, 0x100
	s_addc_u32 s67, s67, 0
	s_add_u32 s73, s73, 0x100
	s_addc_u32 s76, s76, 0
	s_cmp_gt_u32 s77, 29
	s_cbranch_scc0 .LBB0_173
	s_and_b64 vcc, exec, s[20:21]
	s_cbranch_vccz .LBB0_176
	s_barrier

.LBB0_258:
	ds_read_b128 v[152:155], v149
	ds_read_b128 v[156:159], v149 offset:1024
	ds_read_b128 v[160:163], v149 offset:2048
	ds_read_b128 v[164:167], v149 offset:3072
	ds_read_b128 v[168:171], v150
	ds_read_b128 v[172:175], v150 offset:1024
	ds_read_b128 v[176:179], v150 offset:2048
	ds_read_b128 v[180:183], v150 offset:3072
	s_add_u32 s36, s22, 0x100
	s_addc_u32 s37, s23, 0
	s_cmpk_eq_i32 s62, 0xa8
	s_cselect_b32 s57, s5, s37
	s_cselect_b32 s56, s4, s36
	s_cselect_b32 s41, s21, s61
	s_cselect_b32 s40, s20, s60
	s_add_i32 m0, s25, 0xc000
	ds_read_b128 v[184:187], v151
	ds_read_b128 v[188:191], v151 offset:1024
	ds_read_b128 v[192:195], v151 offset:2048
	ds_read_b128 v[196:199], v151 offset:3072
	ds_read_b128 v[200:203], v151 offset:4096
	ds_read_b128 v[204:207], v151 offset:5120
	ds_read_b128 v[208:211], v151 offset:6144
	ds_read_b128 v[212:215], v151 offset:7168
	global_load_lds_dwordx4 v136, s[22:23]
	s_add_i32 m0, s25, 0xe000
	s_nop 0
	global_load_lds_dwordx4 v138, s[22:23]
	s_waitcnt vmcnt(8)
	s_waitcnt lgkmcnt(0)
	s_setprio 1
	s_barrier
	v_mfma_f32_16x16x32_bf16 v[124:127], v[152:155], v[184:187], v[124:127]
	v_mfma_f32_16x16x32_bf16 v[120:123], v[160:163], v[184:187], v[120:123]
	v_mfma_f32_16x16x32_bf16 v[116:119], v[152:155], v[192:195], v[116:119]
	v_mfma_f32_16x16x32_bf16 v[108:111], v[160:163], v[192:195], v[108:111]
	v_mfma_f32_16x16x32_bf16 v[100:103], v[152:155], v[200:203], v[100:103]
	v_mfma_f32_16x16x32_bf16 v[92:95], v[160:163], v[200:203], v[92:95]
	v_mfma_f32_16x16x32_bf16 v[84:87], v[152:155], v[208:211], v[84:87]
	v_mfma_f32_16x16x32_bf16 v[76:79], v[160:163], v[208:211], v[76:79]
	v_mfma_f32_16x16x32_bf16 v[124:127], v[156:159], v[188:191], v[124:127]
	v_mfma_f32_16x16x32_bf16 v[120:123], v[164:167], v[188:191], v[120:123]
	v_mfma_f32_16x16x32_bf16 v[116:119], v[156:159], v[196:199], v[116:119]
	v_mfma_f32_16x16x32_bf16 v[108:111], v[164:167], v[196:199], v[108:111]
	v_mfma_f32_16x16x32_bf16 v[100:103], v[156:159], v[204:207], v[100:103]
	v_mfma_f32_16x16x32_bf16 v[92:95], v[164:167], v[204:207], v[92:95]
	v_mfma_f32_16x16x32_bf16 v[84:87], v[156:159], v[212:215], v[84:87]
	v_mfma_f32_16x16x32_bf16 v[76:79], v[164:167], v[212:215], v[76:79]
	v_mfma_f32_16x16x32_bf16 v[112:115], v[168:171], v[184:187], v[112:115]
	v_mfma_f32_16x16x32_bf16 v[104:107], v[176:179], v[184:187], v[104:107]
	v_mfma_f32_16x16x32_bf16 v[96:99], v[168:171], v[192:195], v[96:99]
	v_mfma_f32_16x16x32_bf16 v[88:91], v[176:179], v[192:195], v[88:91]
	v_mfma_f32_16x16x32_bf16 v[80:83], v[168:171], v[200:203], v[80:83]
	v_mfma_f32_16x16x32_bf16 v[72:75], v[176:179], v[200:203], v[72:75]
	v_mfma_f32_16x16x32_bf16 v[68:71], v[168:171], v[208:211], v[68:71]
	v_mfma_f32_16x16x32_bf16 v[64:67], v[176:179], v[208:211], v[64:67]
	v_mfma_f32_16x16x32_bf16 v[112:115], v[172:175], v[188:191], v[112:115]
	v_mfma_f32_16x16x32_bf16 v[104:107], v[180:183], v[188:191], v[104:107]
	v_mfma_f32_16x16x32_bf16 v[96:99], v[172:175], v[196:199], v[96:99]
	v_mfma_f32_16x16x32_bf16 v[88:91], v[180:183], v[196:199], v[88:91]
	v_mfma_f32_16x16x32_bf16 v[80:83], v[172:175], v[204:207], v[80:83]
	v_mfma_f32_16x16x32_bf16 v[72:75], v[180:183], v[204:207], v[72:75]
	v_mfma_f32_16x16x32_bf16 v[68:71], v[172:175], v[212:215], v[68:71]
	v_mfma_f32_16x16x32_bf16 v[64:67], v[180:183], v[212:215], v[64:67]
	s_barrier
	s_setprio 0
	s_add_i32 s22, s35, s3
	s_mov_b32 m0, s22
	ds_read_b128 v[184:187], v151 offset:16384
	ds_read_b128 v[188:191], v151 offset:17408
	ds_read_b128 v[192:195], v151 offset:18432
	ds_read_b128 v[196:199], v151 offset:19456
	ds_read_b128 v[200:203], v151 offset:20480
	ds_read_b128 v[204:207], v151 offset:21504
	ds_read_b128 v[208:211], v151 offset:22528
	ds_read_b128 v[212:215], v151 offset:23552
	global_load_lds_dwordx4 v132, s[40:41]
	s_add_i32 m0, s22, 0x2000
	s_add_u32 s22, s40, 0x2b0000
	s_mov_b64 s[98:99], s[40:41]
	s_addc_u32 s23, s41, 0
	s_add_i32 s63, s52, s3
	global_load_lds_dwordx4 v128, s[98:99]
	s_mov_b32 m0, s63
	s_nop 0
	global_load_lds_dwordx4 v132, s[22:23]
	s_add_i32 m0, s63, 0x2000
	s_nop 0
	global_load_lds_dwordx4 v128, s[22:23]
	s_mov_b32 m0, s25
	s_nop 0
	global_load_lds_dwordx4 v134, s[56:57]
	s_mov_b32 m0, s26
	s_nop 0
	global_load_lds_dwordx4 v130, s[56:57]
	s_waitcnt vmcnt(8)
	s_waitcnt lgkmcnt(0)
	s_setprio 1
	s_barrier
	v_mfma_f32_16x16x32_bf16 v[60:63], v[152:155], v[184:187], v[60:63]
	v_mfma_f32_16x16x32_bf16 v[56:59], v[160:163], v[184:187], v[56:59]
	v_mfma_f32_16x16x32_bf16 v[52:55], v[152:155], v[192:195], v[52:55]
	v_mfma_f32_16x16x32_bf16 v[44:47], v[160:163], v[192:195], v[44:47]
	v_mfma_f32_16x16x32_bf16 v[36:39], v[152:155], v[200:203], v[36:39]
	v_mfma_f32_16x16x32_bf16 v[28:31], v[160:163], v[200:203], v[28:31]
	v_mfma_f32_16x16x32_bf16 v[20:23], v[152:155], v[208:211], v[20:23]
	v_mfma_f32_16x16x32_bf16 v[12:15], v[160:163], v[208:211], v[12:15]
	v_mfma_f32_16x16x32_bf16 v[60:63], v[156:159], v[188:191], v[60:63]
	v_mfma_f32_16x16x32_bf16 v[56:59], v[164:167], v[188:191], v[56:59]
	v_mfma_f32_16x16x32_bf16 v[52:55], v[156:159], v[196:199], v[52:55]
	v_mfma_f32_16x16x32_bf16 v[44:47], v[164:167], v[196:199], v[44:47]
	v_mfma_f32_16x16x32_bf16 v[36:39], v[156:159], v[204:207], v[36:39]
	v_mfma_f32_16x16x32_bf16 v[28:31], v[164:167], v[204:207], v[28:31]
	v_mfma_f32_16x16x32_bf16 v[20:23], v[156:159], v[212:215], v[20:23]
	v_mfma_f32_16x16x32_bf16 v[12:15], v[164:167], v[212:215], v[12:15]
	v_mfma_f32_16x16x32_bf16 v[48:51], v[168:171], v[184:187], v[48:51]
	v_mfma_f32_16x16x32_bf16 v[40:43], v[176:179], v[184:187], v[40:43]
	v_mfma_f32_16x16x32_bf16 v[32:35], v[168:171], v[192:195], v[32:35]
	v_mfma_f32_16x16x32_bf16 v[24:27], v[176:179], v[192:195], v[24:27]
	v_mfma_f32_16x16x32_bf16 v[16:19], v[168:171], v[200:203], v[16:19]
	v_mfma_f32_16x16x32_bf16 v[8:11], v[176:179], v[200:203], v[8:11]
	v_mfma_f32_16x16x32_bf16 v[4:7], v[168:171], v[208:211], v[4:7]
	v_mfma_f32_16x16x32_bf16 v[0:3], v[176:179], v[208:211], v[0:3]
	v_mfma_f32_16x16x32_bf16 v[48:51], v[172:175], v[188:191], v[48:51]
	v_mfma_f32_16x16x32_bf16 v[40:43], v[180:183], v[188:191], v[40:43]
	v_mfma_f32_16x16x32_bf16 v[32:35], v[172:175], v[196:199], v[32:35]
	v_mfma_f32_16x16x32_bf16 v[24:27], v[180:183], v[196:199], v[24:27]
	v_mfma_f32_16x16x32_bf16 v[16:19], v[172:175], v[204:207], v[16:19]
	v_mfma_f32_16x16x32_bf16 v[8:11], v[180:183], v[204:207], v[8:11]
	v_mfma_f32_16x16x32_bf16 v[4:7], v[172:175], v[212:215], v[4:7]
	v_mfma_f32_16x16x32_bf16 v[0:3], v[180:183], v[212:215], v[0:3]
	s_barrier
	s_setprio 0
	s_add_i32 s63, 0, 0x18000
	s_add_i32 s64, 0, 0x1c000
	v_add_u32_e32 v164, s63, v147
	v_add_u32_e32 v180, s64, v147
	ds_read_b128 v[152:155], v164
	ds_read_b128 v[156:159], v164 offset:1024
	ds_read_b128 v[160:163], v164 offset:2048
	ds_read_b128 v[164:167], v164 offset:3072
	ds_read_b128 v[168:171], v180
	ds_read_b128 v[172:175], v180 offset:1024
	ds_read_b128 v[176:179], v180 offset:2048
	ds_read_b128 v[180:183], v180 offset:3072
	s_add_u32 s22, s56, 0x2b0000
	s_addc_u32 s23, s57, 0
	s_mov_b32 m0, s27
	ds_read_b128 v[184:187], v151 offset:32768
	ds_read_b128 v[188:191], v151 offset:33792
	ds_read_b128 v[192:195], v151 offset:34816
	ds_read_b128 v[196:199], v151 offset:35840
	ds_read_b128 v[200:203], v151 offset:36864
	ds_read_b128 v[204:207], v151 offset:37888
	ds_read_b128 v[208:211], v151 offset:38912
	ds_read_b128 v[212:215], v151 offset:39936
	global_load_lds_dwordx4 v134, s[22:23]
	s_mov_b32 m0, s28
	s_nop 0
	global_load_lds_dwordx4 v130, s[22:23]
	s_waitcnt vmcnt(8)
	s_waitcnt lgkmcnt(0)
	s_setprio 1
	s_barrier
	v_mfma_f32_16x16x32_bf16 v[124:127], v[152:155], v[184:187], v[124:127]
	v_mfma_f32_16x16x32_bf16 v[120:123], v[160:163], v[184:187], v[120:123]
	v_mfma_f32_16x16x32_bf16 v[116:119], v[152:155], v[192:195], v[116:119]
	v_mfma_f32_16x16x32_bf16 v[108:111], v[160:163], v[192:195], v[108:111]
	v_mfma_f32_16x16x32_bf16 v[100:103], v[152:155], v[200:203], v[100:103]
	v_mfma_f32_16x16x32_bf16 v[92:95], v[160:163], v[200:203], v[92:95]
	v_mfma_f32_16x16x32_bf16 v[84:87], v[152:155], v[208:211], v[84:87]
	v_mfma_f32_16x16x32_bf16 v[76:79], v[160:163], v[208:211], v[76:79]
	v_mfma_f32_16x16x32_bf16 v[124:127], v[156:159], v[188:191], v[124:127]
	v_mfma_f32_16x16x32_bf16 v[120:123], v[164:167], v[188:191], v[120:123]
	v_mfma_f32_16x16x32_bf16 v[116:119], v[156:159], v[196:199], v[116:119]
	v_mfma_f32_16x16x32_bf16 v[108:111], v[164:167], v[196:199], v[108:111]
	v_mfma_f32_16x16x32_bf16 v[100:103], v[156:159], v[204:207], v[100:103]
	v_mfma_f32_16x16x32_bf16 v[92:95], v[164:167], v[204:207], v[92:95]
	v_mfma_f32_16x16x32_bf16 v[84:87], v[156:159], v[212:215], v[84:87]
	v_mfma_f32_16x16x32_bf16 v[76:79], v[164:167], v[212:215], v[76:79]
	v_mfma_f32_16x16x32_bf16 v[112:115], v[168:171], v[184:187], v[112:115]
	v_mfma_f32_16x16x32_bf16 v[104:107], v[176:179], v[184:187], v[104:107]
	v_mfma_f32_16x16x32_bf16 v[96:99], v[168:171], v[192:195], v[96:99]
	v_mfma_f32_16x16x32_bf16 v[88:91], v[176:179], v[192:195], v[88:91]
	v_mfma_f32_16x16x32_bf16 v[80:83], v[168:171], v[200:203], v[80:83]
	v_mfma_f32_16x16x32_bf16 v[72:75], v[176:179], v[200:203], v[72:75]
	v_mfma_f32_16x16x32_bf16 v[68:71], v[168:171], v[208:211], v[68:71]
	v_mfma_f32_16x16x32_bf16 v[64:67], v[176:179], v[208:211], v[64:67]
	v_mfma_f32_16x16x32_bf16 v[112:115], v[172:175], v[188:191], v[112:115]
	v_mfma_f32_16x16x32_bf16 v[104:107], v[180:183], v[188:191], v[104:107]
	v_mfma_f32_16x16x32_bf16 v[96:99], v[172:175], v[196:199], v[96:99]
	v_mfma_f32_16x16x32_bf16 v[88:91], v[180:183], v[196:199], v[88:91]
	v_mfma_f32_16x16x32_bf16 v[80:83], v[172:175], v[204:207], v[80:83]
	v_mfma_f32_16x16x32_bf16 v[72:75], v[180:183], v[204:207], v[72:75]
	v_mfma_f32_16x16x32_bf16 v[68:71], v[172:175], v[212:215], v[68:71]
	v_mfma_f32_16x16x32_bf16 v[64:67], v[180:183], v[212:215], v[64:67]
	s_barrier
	s_setprio 0
	s_add_i32 s22, s63, s3
	s_add_i32 m0, s22, -128
	ds_read_b128 v[184:187], v151 offset:49152
	ds_read_b128 v[188:191], v151 offset:50176
	ds_read_b128 v[192:195], v151 offset:51200
	ds_read_b128 v[196:199], v151 offset:52224
	ds_read_b128 v[200:203], v151 offset:53248
	ds_read_b128 v[204:207], v151 offset:54272
	ds_read_b128 v[208:211], v151 offset:55296
	ds_read_b128 v[212:215], v151 offset:56320
	global_load_lds_dwordx4 v132, s[40:41] offset:128
	s_add_i32 m0, s22, 8064
	s_add_u32 s22, s40, 0x2b0080
	s_addc_u32 s23, s41, 0
	s_add_i32 s40, s64, s3
	global_load_lds_dwordx4 v128, s[98:99] offset:128
	s_mov_b32 m0, s40
	s_nop 0
	global_load_lds_dwordx4 v132, s[22:23]
	s_add_i32 m0, s40, 0x2000
	s_nop 0
	global_load_lds_dwordx4 v128, s[22:23]
	s_add_i32 m0, s31, -128
	s_nop 0
	global_load_lds_dwordx4 v134, s[56:57] offset:128
	s_add_i32 m0, s33, -128
	s_nop 0
	global_load_lds_dwordx4 v130, s[56:57] offset:128
	s_waitcnt vmcnt(8)
	s_waitcnt lgkmcnt(0)
	s_setprio 1
	s_barrier
	v_mfma_f32_16x16x32_bf16 v[60:63], v[152:155], v[184:187], v[60:63]
	v_mfma_f32_16x16x32_bf16 v[56:59], v[160:163], v[184:187], v[56:59]
	v_mfma_f32_16x16x32_bf16 v[52:55], v[152:155], v[192:195], v[52:55]
	v_mfma_f32_16x16x32_bf16 v[44:47], v[160:163], v[192:195], v[44:47]
	v_mfma_f32_16x16x32_bf16 v[36:39], v[152:155], v[200:203], v[36:39]
	v_mfma_f32_16x16x32_bf16 v[28:31], v[160:163], v[200:203], v[28:31]
	v_mfma_f32_16x16x32_bf16 v[20:23], v[152:155], v[208:211], v[20:23]
	v_mfma_f32_16x16x32_bf16 v[12:15], v[160:163], v[208:211], v[12:15]
	v_mfma_f32_16x16x32_bf16 v[60:63], v[156:159], v[188:191], v[60:63]
	v_mfma_f32_16x16x32_bf16 v[56:59], v[164:167], v[188:191], v[56:59]
	v_mfma_f32_16x16x32_bf16 v[52:55], v[156:159], v[196:199], v[52:55]
	v_mfma_f32_16x16x32_bf16 v[44:47], v[164:167], v[196:199], v[44:47]
	v_mfma_f32_16x16x32_bf16 v[36:39], v[156:159], v[204:207], v[36:39]
	v_mfma_f32_16x16x32_bf16 v[28:31], v[164:167], v[204:207], v[28:31]
	v_mfma_f32_16x16x32_bf16 v[20:23], v[156:159], v[212:215], v[20:23]
	v_mfma_f32_16x16x32_bf16 v[12:15], v[164:167], v[212:215], v[12:15]
	v_mfma_f32_16x16x32_bf16 v[48:51], v[168:171], v[184:187], v[48:51]
	v_mfma_f32_16x16x32_bf16 v[40:43], v[176:179], v[184:187], v[40:43]
	v_mfma_f32_16x16x32_bf16 v[32:35], v[168:171], v[192:195], v[32:35]
	v_mfma_f32_16x16x32_bf16 v[24:27], v[176:179], v[192:195], v[24:27]
	v_mfma_f32_16x16x32_bf16 v[16:19], v[168:171], v[200:203], v[16:19]
	v_mfma_f32_16x16x32_bf16 v[8:11], v[176:179], v[200:203], v[8:11]
	v_mfma_f32_16x16x32_bf16 v[4:7], v[168:171], v[208:211], v[4:7]
	v_mfma_f32_16x16x32_bf16 v[0:3], v[176:179], v[208:211], v[0:3]
	v_mfma_f32_16x16x32_bf16 v[48:51], v[172:175], v[188:191], v[48:51]
	v_mfma_f32_16x16x32_bf16 v[40:43], v[180:183], v[188:191], v[40:43]
	v_mfma_f32_16x16x32_bf16 v[32:35], v[172:175], v[196:199], v[32:35]
	v_mfma_f32_16x16x32_bf16 v[24:27], v[180:183], v[196:199], v[24:27]
	v_mfma_f32_16x16x32_bf16 v[16:19], v[172:175], v[204:207], v[16:19]
	v_mfma_f32_16x16x32_bf16 v[8:11], v[180:183], v[204:207], v[8:11]
	v_mfma_f32_16x16x32_bf16 v[4:7], v[172:175], v[212:215], v[4:7]
	v_mfma_f32_16x16x32_bf16 v[0:3], v[180:183], v[212:215], v[0:3]
	s_barrier
	s_setprio 0
	s_add_i32 s62, s62, 2
	s_add_u32 s60, s60, 0x100
	s_addc_u32 s61, s61, 0
	s_cmpk_gt_u32 s62, 0xa9
	s_mov_b64 s[22:23], s[36:37]
	s_cbranch_scc0 .LBB0_258
	s_and_b64 vcc, exec, s[14:15]
	s_cbranch_vccz .LBB0_261
	s_barrier

.LBB0_394:
	ds_read_b128 v[156:159], v152
	ds_read_b128 v[160:163], v152 offset:1024
	ds_read_b128 v[164:167], v152 offset:2048
	ds_read_b128 v[168:171], v152 offset:3072
	ds_read_b128 v[172:175], v153
	ds_read_b128 v[176:179], v153 offset:1024
	ds_read_b128 v[180:183], v153 offset:2048
	ds_read_b128 v[184:187], v153 offset:3072
	s_add_u32 s40, s38, 0xfff00080
	s_addc_u32 s41, s39, -1
	s_cmp_eq_u32 s64, 60
	s_cselect_b32 s57, s21, s41
	s_cselect_b32 s56, s60, s40
	s_cselect_b32 s41, s15, s63
	s_cselect_b32 s40, s61, s62
	s_add_i32 m0, s29, 0xc000
	ds_read_b128 v[188:191], v154
	ds_read_b128 v[192:195], v154 offset:1024
	ds_read_b128 v[196:199], v154 offset:2048
	ds_read_b128 v[200:203], v154 offset:3072
	ds_read_b128 v[204:207], v154 offset:4096
	ds_read_b128 v[208:211], v154 offset:5120
	ds_read_b128 v[212:215], v154 offset:6144
	ds_read_b128 v[216:219], v154 offset:7168
	global_load_lds_dwordx4 v140, s[38:39]
	s_add_i32 m0, s29, 0xe000
	s_nop 0
	global_load_lds_dwordx4 v142, s[38:39]
	s_waitcnt vmcnt(8)
	s_waitcnt lgkmcnt(0)
	s_setprio 1
	s_barrier
	v_mfma_f32_16x16x32_bf16 v[124:127], v[156:159], v[188:191], v[124:127]
	v_mfma_f32_16x16x32_bf16 v[120:123], v[164:167], v[188:191], v[120:123]
	v_mfma_f32_16x16x32_bf16 v[112:115], v[156:159], v[196:199], v[112:115]
	v_mfma_f32_16x16x32_bf16 v[104:107], v[164:167], v[196:199], v[104:107]
	v_mfma_f32_16x16x32_bf16 v[96:99], v[156:159], v[204:207], v[96:99]
	v_mfma_f32_16x16x32_bf16 v[88:91], v[164:167], v[204:207], v[88:91]
	v_mfma_f32_16x16x32_bf16 v[80:83], v[156:159], v[212:215], v[80:83]
	v_mfma_f32_16x16x32_bf16 v[72:75], v[164:167], v[212:215], v[72:75]
	v_mfma_f32_16x16x32_bf16 v[124:127], v[160:163], v[192:195], v[124:127]
	v_mfma_f32_16x16x32_bf16 v[120:123], v[168:171], v[192:195], v[120:123]
	v_mfma_f32_16x16x32_bf16 v[112:115], v[160:163], v[200:203], v[112:115]
	v_mfma_f32_16x16x32_bf16 v[104:107], v[168:171], v[200:203], v[104:107]
	v_mfma_f32_16x16x32_bf16 v[96:99], v[160:163], v[208:211], v[96:99]
	v_mfma_f32_16x16x32_bf16 v[88:91], v[168:171], v[208:211], v[88:91]
	v_mfma_f32_16x16x32_bf16 v[80:83], v[160:163], v[216:219], v[80:83]
	v_mfma_f32_16x16x32_bf16 v[72:75], v[168:171], v[216:219], v[72:75]
	v_mfma_f32_16x16x32_bf16 v[116:119], v[172:175], v[188:191], v[116:119]
	v_mfma_f32_16x16x32_bf16 v[108:111], v[180:183], v[188:191], v[108:111]
	v_mfma_f32_16x16x32_bf16 v[100:103], v[172:175], v[196:199], v[100:103]
	v_mfma_f32_16x16x32_bf16 v[92:95], v[180:183], v[196:199], v[92:95]
	v_mfma_f32_16x16x32_bf16 v[84:87], v[172:175], v[204:207], v[84:87]
	v_mfma_f32_16x16x32_bf16 v[76:79], v[180:183], v[204:207], v[76:79]
	v_mfma_f32_16x16x32_bf16 v[68:71], v[172:175], v[212:215], v[68:71]
	v_mfma_f32_16x16x32_bf16 v[64:67], v[180:183], v[212:215], v[64:67]
	v_mfma_f32_16x16x32_bf16 v[116:119], v[176:179], v[192:195], v[116:119]
	v_mfma_f32_16x16x32_bf16 v[108:111], v[184:187], v[192:195], v[108:111]
	v_mfma_f32_16x16x32_bf16 v[100:103], v[176:179], v[200:203], v[100:103]
	v_mfma_f32_16x16x32_bf16 v[92:95], v[184:187], v[200:203], v[92:95]
	v_mfma_f32_16x16x32_bf16 v[84:87], v[176:179], v[208:211], v[84:87]
	v_mfma_f32_16x16x32_bf16 v[76:79], v[184:187], v[208:211], v[76:79]
	v_mfma_f32_16x16x32_bf16 v[68:71], v[176:179], v[216:219], v[68:71]
	v_mfma_f32_16x16x32_bf16 v[64:67], v[184:187], v[216:219], v[64:67]
	s_barrier
	s_setprio 0
	s_add_i32 s65, s58, s24
	s_mov_b32 m0, s65
	ds_read_b128 v[188:191], v154 offset:16384
	ds_read_b128 v[192:195], v154 offset:17408
	ds_read_b128 v[196:199], v154 offset:18432
	ds_read_b128 v[200:203], v154 offset:19456
	ds_read_b128 v[204:207], v154 offset:20480
	ds_read_b128 v[208:211], v154 offset:21504
	ds_read_b128 v[212:215], v154 offset:22528
	ds_read_b128 v[216:219], v154 offset:23552
	global_load_lds_dwordx4 v132, s[40:41]
	s_add_i32 m0, s65, 0x2000
	s_add_u32 s66, s40, 0x100000
	s_mov_b64 s[98:99], s[40:41]
	s_addc_u32 s67, s41, 0
	s_add_i32 s65, s59, s24
	global_load_lds_dwordx4 v128, s[98:99]
	s_mov_b32 m0, s65
	s_mov_b64 s[100:101], s[56:57]
	global_load_lds_dwordx4 v132, s[66:67]
	s_add_i32 m0, s65, 0x2000
	s_nop 0
	global_load_lds_dwordx4 v128, s[66:67]
	s_mov_b64 s[100:101], s[56:57]
	s_mov_b32 m0, s29
	s_nop 0
	global_load_lds_dwordx4 v134, s[100:101]
	s_mov_b32 m0, s30
	s_nop 0
	global_load_lds_dwordx4 v130, s[100:101]
	s_waitcnt vmcnt(8)
	s_waitcnt lgkmcnt(0)
	s_setprio 1
	s_barrier
	v_mfma_f32_16x16x32_bf16 v[60:63], v[156:159], v[188:191], v[60:63]
	v_mfma_f32_16x16x32_bf16 v[56:59], v[164:167], v[188:191], v[56:59]
	v_mfma_f32_16x16x32_bf16 v[52:55], v[156:159], v[196:199], v[52:55]
	v_mfma_f32_16x16x32_bf16 v[44:47], v[164:167], v[196:199], v[44:47]
	v_mfma_f32_16x16x32_bf16 v[36:39], v[156:159], v[204:207], v[36:39]
	v_mfma_f32_16x16x32_bf16 v[28:31], v[164:167], v[204:207], v[28:31]
	v_mfma_f32_16x16x32_bf16 v[20:23], v[156:159], v[212:215], v[20:23]
	v_mfma_f32_16x16x32_bf16 v[12:15], v[164:167], v[212:215], v[12:15]
	v_mfma_f32_16x16x32_bf16 v[60:63], v[160:163], v[192:195], v[60:63]
	v_mfma_f32_16x16x32_bf16 v[56:59], v[168:171], v[192:195], v[56:59]
	v_mfma_f32_16x16x32_bf16 v[52:55], v[160:163], v[200:203], v[52:55]
	v_mfma_f32_16x16x32_bf16 v[44:47], v[168:171], v[200:203], v[44:47]
	v_mfma_f32_16x16x32_bf16 v[36:39], v[160:163], v[208:211], v[36:39]
	v_mfma_f32_16x16x32_bf16 v[28:31], v[168:171], v[208:211], v[28:31]
	v_mfma_f32_16x16x32_bf16 v[20:23], v[160:163], v[216:219], v[20:23]
	v_mfma_f32_16x16x32_bf16 v[12:15], v[168:171], v[216:219], v[12:15]
	v_mfma_f32_16x16x32_bf16 v[48:51], v[172:175], v[188:191], v[48:51]
	v_mfma_f32_16x16x32_bf16 v[40:43], v[180:183], v[188:191], v[40:43]
	v_mfma_f32_16x16x32_bf16 v[32:35], v[172:175], v[196:199], v[32:35]
	v_mfma_f32_16x16x32_bf16 v[24:27], v[180:183], v[196:199], v[24:27]
	v_mfma_f32_16x16x32_bf16 v[16:19], v[172:175], v[204:207], v[16:19]
	v_mfma_f32_16x16x32_bf16 v[8:11], v[180:183], v[204:207], v[8:11]
	v_mfma_f32_16x16x32_bf16 v[4:7], v[172:175], v[212:215], v[4:7]
	v_mfma_f32_16x16x32_bf16 v[0:3], v[180:183], v[212:215], v[0:3]
	v_mfma_f32_16x16x32_bf16 v[48:51], v[176:179], v[192:195], v[48:51]
	v_mfma_f32_16x16x32_bf16 v[40:43], v[184:187], v[192:195], v[40:43]
	v_mfma_f32_16x16x32_bf16 v[32:35], v[176:179], v[200:203], v[32:35]
	v_mfma_f32_16x16x32_bf16 v[24:27], v[184:187], v[200:203], v[24:27]
	v_mfma_f32_16x16x32_bf16 v[16:19], v[176:179], v[208:211], v[16:19]
	v_mfma_f32_16x16x32_bf16 v[8:11], v[184:187], v[208:211], v[8:11]
	v_mfma_f32_16x16x32_bf16 v[4:7], v[176:179], v[216:219], v[4:7]
	v_mfma_f32_16x16x32_bf16 v[0:3], v[184:187], v[216:219], v[0:3]
	s_barrier
	s_setprio 0
	s_add_i32 s65, 0, 0x18000
	v_add_u32_e32 v155, s65, v151
	s_add_i32 s66, 0, 0x1c000
	ds_read_b128 v[156:159], v155
	ds_read_b128 v[160:163], v155 offset:1024
	ds_read_b128 v[164:167], v155 offset:2048
	ds_read_b128 v[168:171], v155 offset:3072
	v_add_u32_e32 v155, s66, v151
	ds_read_b128 v[172:175], v155
	ds_read_b128 v[176:179], v155 offset:1024
	ds_read_b128 v[180:183], v155 offset:2048
	ds_read_b128 v[184:187], v155 offset:3072
	s_add_u32 s56, s56, 0x100000
	s_addc_u32 s57, s57, 0
	s_mov_b32 m0, s31
	ds_read_b128 v[188:191], v154 offset:32768
	ds_read_b128 v[192:195], v154 offset:33792
	ds_read_b128 v[196:199], v154 offset:34816
	ds_read_b128 v[200:203], v154 offset:35840
	ds_read_b128 v[204:207], v154 offset:36864
	ds_read_b128 v[208:211], v154 offset:37888
	ds_read_b128 v[212:215], v154 offset:38912
	ds_read_b128 v[216:219], v154 offset:39936
	global_load_lds_dwordx4 v134, s[56:57]
	s_mov_b32 m0, s33
	s_nop 0
	global_load_lds_dwordx4 v130, s[56:57]
	s_waitcnt vmcnt(8)
	s_waitcnt lgkmcnt(0)
	s_setprio 1
	s_barrier
	v_mfma_f32_16x16x32_bf16 v[124:127], v[156:159], v[188:191], v[124:127]
	v_mfma_f32_16x16x32_bf16 v[120:123], v[164:167], v[188:191], v[120:123]
	v_mfma_f32_16x16x32_bf16 v[112:115], v[156:159], v[196:199], v[112:115]
	v_mfma_f32_16x16x32_bf16 v[104:107], v[164:167], v[196:199], v[104:107]
	v_mfma_f32_16x16x32_bf16 v[96:99], v[156:159], v[204:207], v[96:99]
	v_mfma_f32_16x16x32_bf16 v[88:91], v[164:167], v[204:207], v[88:91]
	v_mfma_f32_16x16x32_bf16 v[80:83], v[156:159], v[212:215], v[80:83]
	v_mfma_f32_16x16x32_bf16 v[72:75], v[164:167], v[212:215], v[72:75]
	v_mfma_f32_16x16x32_bf16 v[124:127], v[160:163], v[192:195], v[124:127]
	v_mfma_f32_16x16x32_bf16 v[120:123], v[168:171], v[192:195], v[120:123]
	v_mfma_f32_16x16x32_bf16 v[112:115], v[160:163], v[200:203], v[112:115]
	v_mfma_f32_16x16x32_bf16 v[104:107], v[168:171], v[200:203], v[104:107]
	v_mfma_f32_16x16x32_bf16 v[96:99], v[160:163], v[208:211], v[96:99]
	v_mfma_f32_16x16x32_bf16 v[88:91], v[168:171], v[208:211], v[88:91]
	v_mfma_f32_16x16x32_bf16 v[80:83], v[160:163], v[216:219], v[80:83]
	v_mfma_f32_16x16x32_bf16 v[72:75], v[168:171], v[216:219], v[72:75]
	v_mfma_f32_16x16x32_bf16 v[116:119], v[172:175], v[188:191], v[116:119]
	v_mfma_f32_16x16x32_bf16 v[108:111], v[180:183], v[188:191], v[108:111]
	v_mfma_f32_16x16x32_bf16 v[100:103], v[172:175], v[196:199], v[100:103]
	v_mfma_f32_16x16x32_bf16 v[92:95], v[180:183], v[196:199], v[92:95]
	v_mfma_f32_16x16x32_bf16 v[84:87], v[172:175], v[204:207], v[84:87]
	v_mfma_f32_16x16x32_bf16 v[76:79], v[180:183], v[204:207], v[76:79]
	v_mfma_f32_16x16x32_bf16 v[68:71], v[172:175], v[212:215], v[68:71]
	v_mfma_f32_16x16x32_bf16 v[64:67], v[180:183], v[212:215], v[64:67]
	v_mfma_f32_16x16x32_bf16 v[116:119], v[176:179], v[192:195], v[116:119]
	v_mfma_f32_16x16x32_bf16 v[108:111], v[184:187], v[192:195], v[108:111]
	v_mfma_f32_16x16x32_bf16 v[100:103], v[176:179], v[200:203], v[100:103]
	v_mfma_f32_16x16x32_bf16 v[92:95], v[184:187], v[200:203], v[92:95]
	v_mfma_f32_16x16x32_bf16 v[84:87], v[176:179], v[208:211], v[84:87]
	v_mfma_f32_16x16x32_bf16 v[76:79], v[184:187], v[208:211], v[76:79]
	v_mfma_f32_16x16x32_bf16 v[68:71], v[176:179], v[216:219], v[68:71]
	v_mfma_f32_16x16x32_bf16 v[64:67], v[184:187], v[216:219], v[64:67]
	s_barrier
	s_setprio 0
	s_add_i32 s56, s65, s24
	s_add_i32 m0, s56, -128
	ds_read_b128 v[188:191], v154 offset:49152
	ds_read_b128 v[192:195], v154 offset:50176
	ds_read_b128 v[196:199], v154 offset:51200
	ds_read_b128 v[200:203], v154 offset:52224
	ds_read_b128 v[204:207], v154 offset:53248
	ds_read_b128 v[208:211], v154 offset:54272
	ds_read_b128 v[212:215], v154 offset:55296
	ds_read_b128 v[216:219], v154 offset:56320
	global_load_lds_dwordx4 v132, s[40:41] offset:128
	s_add_i32 m0, s56, 8064
	s_add_u32 s40, s40, 0x100080
	s_addc_u32 s41, s41, 0
	s_add_i32 s56, s66, s24
	global_load_lds_dwordx4 v128, s[98:99] offset:128
	s_mov_b32 m0, s56
	s_nop 0
	global_load_lds_dwordx4 v132, s[40:41]
	s_add_i32 m0, s56, 0x2000
	s_nop 0
	global_load_lds_dwordx4 v128, s[40:41]
	s_add_i32 m0, s54, -128
	s_nop 0
	global_load_lds_dwordx4 v134, s[100:101] offset:128
	s_add_i32 m0, s55, -128
	s_nop 0
	global_load_lds_dwordx4 v130, s[100:101] offset:128
	s_waitcnt vmcnt(8)
	s_waitcnt lgkmcnt(0)
	s_setprio 1
	s_barrier
	v_mfma_f32_16x16x32_bf16 v[60:63], v[156:159], v[188:191], v[60:63]
	v_mfma_f32_16x16x32_bf16 v[56:59], v[164:167], v[188:191], v[56:59]
	v_mfma_f32_16x16x32_bf16 v[52:55], v[156:159], v[196:199], v[52:55]
	v_mfma_f32_16x16x32_bf16 v[44:47], v[164:167], v[196:199], v[44:47]
	v_mfma_f32_16x16x32_bf16 v[36:39], v[156:159], v[204:207], v[36:39]
	v_mfma_f32_16x16x32_bf16 v[28:31], v[164:167], v[204:207], v[28:31]
	v_mfma_f32_16x16x32_bf16 v[20:23], v[156:159], v[212:215], v[20:23]
	v_mfma_f32_16x16x32_bf16 v[12:15], v[164:167], v[212:215], v[12:15]
	v_mfma_f32_16x16x32_bf16 v[60:63], v[160:163], v[192:195], v[60:63]
	v_mfma_f32_16x16x32_bf16 v[56:59], v[168:171], v[192:195], v[56:59]
	v_mfma_f32_16x16x32_bf16 v[52:55], v[160:163], v[200:203], v[52:55]
	v_mfma_f32_16x16x32_bf16 v[44:47], v[168:171], v[200:203], v[44:47]
	v_mfma_f32_16x16x32_bf16 v[36:39], v[160:163], v[208:211], v[36:39]
	v_mfma_f32_16x16x32_bf16 v[28:31], v[168:171], v[208:211], v[28:31]
	v_mfma_f32_16x16x32_bf16 v[20:23], v[160:163], v[216:219], v[20:23]
	v_mfma_f32_16x16x32_bf16 v[12:15], v[168:171], v[216:219], v[12:15]
	v_mfma_f32_16x16x32_bf16 v[48:51], v[172:175], v[188:191], v[48:51]
	v_mfma_f32_16x16x32_bf16 v[40:43], v[180:183], v[188:191], v[40:43]
	v_mfma_f32_16x16x32_bf16 v[32:35], v[172:175], v[196:199], v[32:35]
	v_mfma_f32_16x16x32_bf16 v[24:27], v[180:183], v[196:199], v[24:27]
	v_mfma_f32_16x16x32_bf16 v[16:19], v[172:175], v[204:207], v[16:19]
	v_mfma_f32_16x16x32_bf16 v[8:11], v[180:183], v[204:207], v[8:11]
	v_mfma_f32_16x16x32_bf16 v[4:7], v[172:175], v[212:215], v[4:7]
	v_mfma_f32_16x16x32_bf16 v[0:3], v[180:183], v[212:215], v[0:3]
	v_mfma_f32_16x16x32_bf16 v[48:51], v[176:179], v[192:195], v[48:51]
	v_mfma_f32_16x16x32_bf16 v[40:43], v[184:187], v[192:195], v[40:43]
	v_mfma_f32_16x16x32_bf16 v[32:35], v[176:179], v[200:203], v[32:35]
	v_mfma_f32_16x16x32_bf16 v[24:27], v[184:187], v[200:203], v[24:27]
	v_mfma_f32_16x16x32_bf16 v[16:19], v[176:179], v[208:211], v[16:19]
	v_mfma_f32_16x16x32_bf16 v[8:11], v[184:187], v[208:211], v[8:11]
	v_mfma_f32_16x16x32_bf16 v[4:7], v[176:179], v[216:219], v[4:7]
	v_mfma_f32_16x16x32_bf16 v[0:3], v[184:187], v[216:219], v[0:3]
	s_barrier
	s_setprio 0
	s_add_i32 s64, s64, 2
	s_add_u32 s38, s38, 0x100
	s_addc_u32 s39, s39, 0
	s_add_u32 s62, s62, 0x100
	s_addc_u32 s63, s63, 0
	s_cmp_gt_u32 s64, 61
	s_cbranch_scc0 .LBB0_394
	s_and_b64 vcc, exec, s[12:13]
	s_cbranch_vccz .LBB0_397
	s_barrier

.LBB0_622:
	ds_read_b128 v[152:155], v149
	ds_read_b128 v[156:159], v149 offset:1024
	ds_read_b128 v[160:163], v149 offset:2048
	ds_read_b128 v[164:167], v149 offset:3072
	ds_read_b128 v[168:171], v150
	ds_read_b128 v[172:175], v150 offset:1024
	ds_read_b128 v[176:179], v150 offset:2048
	ds_read_b128 v[180:183], v150 offset:3072
	s_add_u32 s42, s40, 0xfff00080
	s_addc_u32 s43, s41, -1
	s_cmp_eq_u32 s61, 60
	s_cselect_b32 s45, s25, s43
	s_cselect_b32 s44, s57, s42
	s_cselect_b32 s43, s23, s60
	s_cselect_b32 s42, s58, s59
	s_add_i32 m0, s31, 0xc000
	ds_read_b128 v[184:187], v151
	ds_read_b128 v[188:191], v151 offset:1024
	ds_read_b128 v[192:195], v151 offset:2048
	ds_read_b128 v[196:199], v151 offset:3072
	ds_read_b128 v[200:203], v151 offset:4096
	ds_read_b128 v[204:207], v151 offset:5120
	ds_read_b128 v[208:211], v151 offset:6144
	ds_read_b128 v[212:215], v151 offset:7168
	global_load_lds_dwordx4 v136, s[40:41]
	s_add_i32 m0, s31, 0xe000
	s_nop 0
	global_load_lds_dwordx4 v138, s[40:41]
	s_waitcnt vmcnt(8)
	s_waitcnt lgkmcnt(0)
	s_setprio 1
	s_barrier
	v_mfma_f32_16x16x32_bf16 v[124:127], v[152:155], v[184:187], v[124:127]
	v_mfma_f32_16x16x32_bf16 v[120:123], v[160:163], v[184:187], v[120:123]
	v_mfma_f32_16x16x32_bf16 v[116:119], v[152:155], v[192:195], v[116:119]
	v_mfma_f32_16x16x32_bf16 v[108:111], v[160:163], v[192:195], v[108:111]
	v_mfma_f32_16x16x32_bf16 v[100:103], v[152:155], v[200:203], v[100:103]
	v_mfma_f32_16x16x32_bf16 v[92:95], v[160:163], v[200:203], v[92:95]
	v_mfma_f32_16x16x32_bf16 v[84:87], v[152:155], v[208:211], v[84:87]
	v_mfma_f32_16x16x32_bf16 v[76:79], v[160:163], v[208:211], v[76:79]
	v_mfma_f32_16x16x32_bf16 v[124:127], v[156:159], v[188:191], v[124:127]
	v_mfma_f32_16x16x32_bf16 v[120:123], v[164:167], v[188:191], v[120:123]
	v_mfma_f32_16x16x32_bf16 v[116:119], v[156:159], v[196:199], v[116:119]
	v_mfma_f32_16x16x32_bf16 v[108:111], v[164:167], v[196:199], v[108:111]
	v_mfma_f32_16x16x32_bf16 v[100:103], v[156:159], v[204:207], v[100:103]
	v_mfma_f32_16x16x32_bf16 v[92:95], v[164:167], v[204:207], v[92:95]
	v_mfma_f32_16x16x32_bf16 v[84:87], v[156:159], v[212:215], v[84:87]
	v_mfma_f32_16x16x32_bf16 v[76:79], v[164:167], v[212:215], v[76:79]
	v_mfma_f32_16x16x32_bf16 v[112:115], v[168:171], v[184:187], v[112:115]
	v_mfma_f32_16x16x32_bf16 v[104:107], v[176:179], v[184:187], v[104:107]
	v_mfma_f32_16x16x32_bf16 v[96:99], v[168:171], v[192:195], v[96:99]
	v_mfma_f32_16x16x32_bf16 v[88:91], v[176:179], v[192:195], v[88:91]
	v_mfma_f32_16x16x32_bf16 v[80:83], v[168:171], v[200:203], v[80:83]
	v_mfma_f32_16x16x32_bf16 v[72:75], v[176:179], v[200:203], v[72:75]
	v_mfma_f32_16x16x32_bf16 v[68:71], v[168:171], v[208:211], v[68:71]
	v_mfma_f32_16x16x32_bf16 v[64:67], v[176:179], v[208:211], v[64:67]
	v_mfma_f32_16x16x32_bf16 v[112:115], v[172:175], v[188:191], v[112:115]
	v_mfma_f32_16x16x32_bf16 v[104:107], v[180:183], v[188:191], v[104:107]
	v_mfma_f32_16x16x32_bf16 v[96:99], v[172:175], v[196:199], v[96:99]
	v_mfma_f32_16x16x32_bf16 v[88:91], v[180:183], v[196:199], v[88:91]
	v_mfma_f32_16x16x32_bf16 v[80:83], v[172:175], v[204:207], v[80:83]
	v_mfma_f32_16x16x32_bf16 v[72:75], v[180:183], v[204:207], v[72:75]
	v_mfma_f32_16x16x32_bf16 v[68:71], v[172:175], v[212:215], v[68:71]
	v_mfma_f32_16x16x32_bf16 v[64:67], v[180:183], v[212:215], v[64:67]
	s_barrier
	s_setprio 0
	s_add_i32 s62, s50, s29
	s_mov_b32 m0, s62
	ds_read_b128 v[184:187], v151 offset:16384
	ds_read_b128 v[188:191], v151 offset:17408
	ds_read_b128 v[192:195], v151 offset:18432
	ds_read_b128 v[196:199], v151 offset:19456
	ds_read_b128 v[200:203], v151 offset:20480
	ds_read_b128 v[204:207], v151 offset:21504
	ds_read_b128 v[208:211], v151 offset:22528
	ds_read_b128 v[212:215], v151 offset:23552
	global_load_lds_dwordx4 v132, s[42:43]
	s_add_i32 m0, s62, 0x2000
	s_add_u32 s62, s42, 0x100000
	s_mov_b64 s[98:99], s[42:43]
	s_addc_u32 s63, s43, 0
	s_add_i32 s64, s51, s29
	global_load_lds_dwordx4 v128, s[98:99]
	s_mov_b32 m0, s64
	s_mov_b64 s[100:101], s[44:45]
	global_load_lds_dwordx4 v132, s[62:63]
	s_add_i32 m0, s64, 0x2000
	s_nop 0
	global_load_lds_dwordx4 v128, s[62:63]
	s_mov_b64 s[100:101], s[44:45]
	s_mov_b32 m0, s31
	s_nop 0
	global_load_lds_dwordx4 v134, s[100:101]
	s_mov_b32 m0, s33
	s_nop 0
	global_load_lds_dwordx4 v130, s[100:101]
	s_waitcnt vmcnt(8)
	s_waitcnt lgkmcnt(0)
	s_setprio 1
	s_barrier
	v_mfma_f32_16x16x32_bf16 v[60:63], v[152:155], v[184:187], v[60:63]
	v_mfma_f32_16x16x32_bf16 v[56:59], v[160:163], v[184:187], v[56:59]
	v_mfma_f32_16x16x32_bf16 v[52:55], v[152:155], v[192:195], v[52:55]
	v_mfma_f32_16x16x32_bf16 v[44:47], v[160:163], v[192:195], v[44:47]
	v_mfma_f32_16x16x32_bf16 v[36:39], v[152:155], v[200:203], v[36:39]
	v_mfma_f32_16x16x32_bf16 v[28:31], v[160:163], v[200:203], v[28:31]
	v_mfma_f32_16x16x32_bf16 v[20:23], v[152:155], v[208:211], v[20:23]
	v_mfma_f32_16x16x32_bf16 v[12:15], v[160:163], v[208:211], v[12:15]
	v_mfma_f32_16x16x32_bf16 v[60:63], v[156:159], v[188:191], v[60:63]
	v_mfma_f32_16x16x32_bf16 v[56:59], v[164:167], v[188:191], v[56:59]
	v_mfma_f32_16x16x32_bf16 v[52:55], v[156:159], v[196:199], v[52:55]
	v_mfma_f32_16x16x32_bf16 v[44:47], v[164:167], v[196:199], v[44:47]
	v_mfma_f32_16x16x32_bf16 v[36:39], v[156:159], v[204:207], v[36:39]
	v_mfma_f32_16x16x32_bf16 v[28:31], v[164:167], v[204:207], v[28:31]
	v_mfma_f32_16x16x32_bf16 v[20:23], v[156:159], v[212:215], v[20:23]
	v_mfma_f32_16x16x32_bf16 v[12:15], v[164:167], v[212:215], v[12:15]
	v_mfma_f32_16x16x32_bf16 v[48:51], v[168:171], v[184:187], v[48:51]
	v_mfma_f32_16x16x32_bf16 v[40:43], v[176:179], v[184:187], v[40:43]
	v_mfma_f32_16x16x32_bf16 v[32:35], v[168:171], v[192:195], v[32:35]
	v_mfma_f32_16x16x32_bf16 v[24:27], v[176:179], v[192:195], v[24:27]
	v_mfma_f32_16x16x32_bf16 v[16:19], v[168:171], v[200:203], v[16:19]
	v_mfma_f32_16x16x32_bf16 v[8:11], v[176:179], v[200:203], v[8:11]
	v_mfma_f32_16x16x32_bf16 v[4:7], v[168:171], v[208:211], v[4:7]
	v_mfma_f32_16x16x32_bf16 v[0:3], v[176:179], v[208:211], v[0:3]
	v_mfma_f32_16x16x32_bf16 v[48:51], v[172:175], v[188:191], v[48:51]
	v_mfma_f32_16x16x32_bf16 v[40:43], v[180:183], v[188:191], v[40:43]
	v_mfma_f32_16x16x32_bf16 v[32:35], v[172:175], v[196:199], v[32:35]
	v_mfma_f32_16x16x32_bf16 v[24:27], v[180:183], v[196:199], v[24:27]
	v_mfma_f32_16x16x32_bf16 v[16:19], v[172:175], v[204:207], v[16:19]
	v_mfma_f32_16x16x32_bf16 v[8:11], v[180:183], v[204:207], v[8:11]
	v_mfma_f32_16x16x32_bf16 v[4:7], v[172:175], v[212:215], v[4:7]
	v_mfma_f32_16x16x32_bf16 v[0:3], v[180:183], v[212:215], v[0:3]
	s_barrier
	s_setprio 0
	s_add_i32 s62, 0, 0x18000
	s_add_i32 s63, 0, 0x1c000
	v_add_u32_e32 v164, s62, v147
	v_add_u32_e32 v180, s63, v147
	ds_read_b128 v[152:155], v164
	ds_read_b128 v[156:159], v164 offset:1024
	ds_read_b128 v[160:163], v164 offset:2048
	ds_read_b128 v[164:167], v164 offset:3072
	ds_read_b128 v[168:171], v180
	ds_read_b128 v[172:175], v180 offset:1024
	ds_read_b128 v[176:179], v180 offset:2048
	ds_read_b128 v[180:183], v180 offset:3072
	s_add_u32 s44, s44, 0x100000
	s_addc_u32 s45, s45, 0
	s_mov_b32 m0, s35
	ds_read_b128 v[184:187], v151 offset:32768
	ds_read_b128 v[188:191], v151 offset:33792
	ds_read_b128 v[192:195], v151 offset:34816
	ds_read_b128 v[196:199], v151 offset:35840
	ds_read_b128 v[200:203], v151 offset:36864
	ds_read_b128 v[204:207], v151 offset:37888
	ds_read_b128 v[208:211], v151 offset:38912
	ds_read_b128 v[212:215], v151 offset:39936
	global_load_lds_dwordx4 v134, s[44:45]
	s_mov_b32 m0, s39
	s_nop 0
	global_load_lds_dwordx4 v130, s[44:45]
	s_waitcnt vmcnt(8)
	s_waitcnt lgkmcnt(0)
	s_setprio 1
	s_barrier
	v_mfma_f32_16x16x32_bf16 v[124:127], v[152:155], v[184:187], v[124:127]
	v_mfma_f32_16x16x32_bf16 v[120:123], v[160:163], v[184:187], v[120:123]
	v_mfma_f32_16x16x32_bf16 v[116:119], v[152:155], v[192:195], v[116:119]
	v_mfma_f32_16x16x32_bf16 v[108:111], v[160:163], v[192:195], v[108:111]
	v_mfma_f32_16x16x32_bf16 v[100:103], v[152:155], v[200:203], v[100:103]
	v_mfma_f32_16x16x32_bf16 v[92:95], v[160:163], v[200:203], v[92:95]
	v_mfma_f32_16x16x32_bf16 v[84:87], v[152:155], v[208:211], v[84:87]
	v_mfma_f32_16x16x32_bf16 v[76:79], v[160:163], v[208:211], v[76:79]
	v_mfma_f32_16x16x32_bf16 v[124:127], v[156:159], v[188:191], v[124:127]
	v_mfma_f32_16x16x32_bf16 v[120:123], v[164:167], v[188:191], v[120:123]
	v_mfma_f32_16x16x32_bf16 v[116:119], v[156:159], v[196:199], v[116:119]
	v_mfma_f32_16x16x32_bf16 v[108:111], v[164:167], v[196:199], v[108:111]
	v_mfma_f32_16x16x32_bf16 v[100:103], v[156:159], v[204:207], v[100:103]
	v_mfma_f32_16x16x32_bf16 v[92:95], v[164:167], v[204:207], v[92:95]
	v_mfma_f32_16x16x32_bf16 v[84:87], v[156:159], v[212:215], v[84:87]
	v_mfma_f32_16x16x32_bf16 v[76:79], v[164:167], v[212:215], v[76:79]
	v_mfma_f32_16x16x32_bf16 v[112:115], v[168:171], v[184:187], v[112:115]
	v_mfma_f32_16x16x32_bf16 v[104:107], v[176:179], v[184:187], v[104:107]
	v_mfma_f32_16x16x32_bf16 v[96:99], v[168:171], v[192:195], v[96:99]
	v_mfma_f32_16x16x32_bf16 v[88:91], v[176:179], v[192:195], v[88:91]
	v_mfma_f32_16x16x32_bf16 v[80:83], v[168:171], v[200:203], v[80:83]
	v_mfma_f32_16x16x32_bf16 v[72:75], v[176:179], v[200:203], v[72:75]
	v_mfma_f32_16x16x32_bf16 v[68:71], v[168:171], v[208:211], v[68:71]
	v_mfma_f32_16x16x32_bf16 v[64:67], v[176:179], v[208:211], v[64:67]
	v_mfma_f32_16x16x32_bf16 v[112:115], v[172:175], v[188:191], v[112:115]
	v_mfma_f32_16x16x32_bf16 v[104:107], v[180:183], v[188:191], v[104:107]
	v_mfma_f32_16x16x32_bf16 v[96:99], v[172:175], v[196:199], v[96:99]
	v_mfma_f32_16x16x32_bf16 v[88:91], v[180:183], v[196:199], v[88:91]
	v_mfma_f32_16x16x32_bf16 v[80:83], v[172:175], v[204:207], v[80:83]
	v_mfma_f32_16x16x32_bf16 v[72:75], v[180:183], v[204:207], v[72:75]
	v_mfma_f32_16x16x32_bf16 v[68:71], v[172:175], v[212:215], v[68:71]
	v_mfma_f32_16x16x32_bf16 v[64:67], v[180:183], v[212:215], v[64:67]
	s_barrier
	s_setprio 0
	s_add_i32 s44, s62, s29
	s_add_i32 m0, s44, -128
	ds_read_b128 v[184:187], v151 offset:49152
	ds_read_b128 v[188:191], v151 offset:50176
	ds_read_b128 v[192:195], v151 offset:51200
	ds_read_b128 v[196:199], v151 offset:52224
	ds_read_b128 v[200:203], v151 offset:53248
	ds_read_b128 v[204:207], v151 offset:54272
	ds_read_b128 v[208:211], v151 offset:55296
	ds_read_b128 v[212:215], v151 offset:56320
	global_load_lds_dwordx4 v132, s[42:43] offset:128
	s_add_i32 m0, s44, 8064
	s_add_u32 s42, s42, 0x100080
	s_addc_u32 s43, s43, 0
	s_add_i32 s44, s63, s29
	global_load_lds_dwordx4 v128, s[98:99] offset:128
	s_mov_b32 m0, s44
	s_nop 0
	global_load_lds_dwordx4 v132, s[42:43]
	s_add_i32 m0, s44, 0x2000
	s_nop 0
	global_load_lds_dwordx4 v128, s[42:43]
	s_add_i32 m0, s48, -128
	s_nop 0
	global_load_lds_dwordx4 v134, s[100:101] offset:128
	s_add_i32 m0, s49, -128
	s_nop 0
	global_load_lds_dwordx4 v130, s[100:101] offset:128
	s_waitcnt vmcnt(8)
	s_waitcnt lgkmcnt(0)
	s_setprio 1
	s_barrier
	v_mfma_f32_16x16x32_bf16 v[60:63], v[152:155], v[184:187], v[60:63]
	v_mfma_f32_16x16x32_bf16 v[56:59], v[160:163], v[184:187], v[56:59]
	v_mfma_f32_16x16x32_bf16 v[52:55], v[152:155], v[192:195], v[52:55]
	v_mfma_f32_16x16x32_bf16 v[44:47], v[160:163], v[192:195], v[44:47]
	v_mfma_f32_16x16x32_bf16 v[36:39], v[152:155], v[200:203], v[36:39]
	v_mfma_f32_16x16x32_bf16 v[28:31], v[160:163], v[200:203], v[28:31]
	v_mfma_f32_16x16x32_bf16 v[20:23], v[152:155], v[208:211], v[20:23]
	v_mfma_f32_16x16x32_bf16 v[12:15], v[160:163], v[208:211], v[12:15]
	v_mfma_f32_16x16x32_bf16 v[60:63], v[156:159], v[188:191], v[60:63]
	v_mfma_f32_16x16x32_bf16 v[56:59], v[164:167], v[188:191], v[56:59]
	v_mfma_f32_16x16x32_bf16 v[52:55], v[156:159], v[196:199], v[52:55]
	v_mfma_f32_16x16x32_bf16 v[44:47], v[164:167], v[196:199], v[44:47]
	v_mfma_f32_16x16x32_bf16 v[36:39], v[156:159], v[204:207], v[36:39]
	v_mfma_f32_16x16x32_bf16 v[28:31], v[164:167], v[204:207], v[28:31]
	v_mfma_f32_16x16x32_bf16 v[20:23], v[156:159], v[212:215], v[20:23]
	v_mfma_f32_16x16x32_bf16 v[12:15], v[164:167], v[212:215], v[12:15]
	v_mfma_f32_16x16x32_bf16 v[48:51], v[168:171], v[184:187], v[48:51]
	v_mfma_f32_16x16x32_bf16 v[40:43], v[176:179], v[184:187], v[40:43]
	v_mfma_f32_16x16x32_bf16 v[32:35], v[168:171], v[192:195], v[32:35]
	v_mfma_f32_16x16x32_bf16 v[24:27], v[176:179], v[192:195], v[24:27]
	v_mfma_f32_16x16x32_bf16 v[16:19], v[168:171], v[200:203], v[16:19]
	v_mfma_f32_16x16x32_bf16 v[8:11], v[176:179], v[200:203], v[8:11]
	v_mfma_f32_16x16x32_bf16 v[4:7], v[168:171], v[208:211], v[4:7]
	v_mfma_f32_16x16x32_bf16 v[0:3], v[176:179], v[208:211], v[0:3]
	v_mfma_f32_16x16x32_bf16 v[48:51], v[172:175], v[188:191], v[48:51]
	v_mfma_f32_16x16x32_bf16 v[40:43], v[180:183], v[188:191], v[40:43]
	v_mfma_f32_16x16x32_bf16 v[32:35], v[172:175], v[196:199], v[32:35]
	v_mfma_f32_16x16x32_bf16 v[24:27], v[180:183], v[196:199], v[24:27]
	v_mfma_f32_16x16x32_bf16 v[16:19], v[172:175], v[204:207], v[16:19]
	v_mfma_f32_16x16x32_bf16 v[8:11], v[180:183], v[204:207], v[8:11]
	v_mfma_f32_16x16x32_bf16 v[4:7], v[172:175], v[212:215], v[4:7]
	v_mfma_f32_16x16x32_bf16 v[0:3], v[180:183], v[212:215], v[0:3]
	s_barrier
	s_setprio 0
	s_add_i32 s61, s61, 2
	s_add_u32 s40, s40, 0x100
	s_addc_u32 s41, s41, 0
	s_add_u32 s59, s59, 0x100
	s_addc_u32 s60, s60, 0
	s_cmp_gt_u32 s61, 61
	s_cbranch_scc0 .LBB0_622
	s_and_b64 vcc, exec, s[10:11]
	s_cbranch_vccz .LBB0_625
	s_barrier

.LBB0_773:
	ds_read_b128 v[144:147], v155
	ds_read_b128 v[148:151], v155 offset:1024
	ds_read_b128 v[158:161], v155 offset:2048
	ds_read_b128 v[162:165], v155 offset:3072
	ds_read_b128 v[166:169], v156
	ds_read_b128 v[170:173], v156 offset:1024
	ds_read_b128 v[174:177], v156 offset:2048
	ds_read_b128 v[178:181], v156 offset:3072
	s_add_u32 s36, s30, 0xfff80080
	s_addc_u32 s37, s31, -1
	s_cmp_eq_u32 s52, 28
	s_cselect_b32 s39, s23, s37
	s_cselect_b32 s38, s48, s36
	s_cselect_b32 s37, s21, s51
	s_cselect_b32 s36, s49, s50
	s_add_i32 m0, s17, 0xc000
	ds_read_b128 v[182:185], v157
	ds_read_b128 v[186:189], v157 offset:1024
	ds_read_b128 v[190:193], v157 offset:2048
	ds_read_b128 v[194:197], v157 offset:3072
	ds_read_b128 v[198:201], v157 offset:4096
	ds_read_b128 v[202:205], v157 offset:5120
	ds_read_b128 v[206:209], v157 offset:6144
	ds_read_b128 v[210:213], v157 offset:7168
	global_load_lds_dwordx4 v136, s[30:31]
	s_add_i32 m0, s17, 0xe000
	s_nop 0
	global_load_lds_dwordx4 v138, s[30:31]
	s_waitcnt vmcnt(8)
	s_waitcnt lgkmcnt(0)
	s_setprio 1
	s_barrier
	v_mfma_i32_16x16x64_i8 v[124:127], v[144:147], v[182:185], v[124:127]
	v_mfma_i32_16x16x64_i8 v[116:119], v[158:161], v[182:185], v[116:119]
	v_mfma_i32_16x16x64_i8 v[108:111], v[144:147], v[190:193], v[108:111]
	v_mfma_i32_16x16x64_i8 v[100:103], v[158:161], v[190:193], v[100:103]
	v_mfma_i32_16x16x64_i8 v[92:95], v[144:147], v[198:201], v[92:95]
	v_mfma_i32_16x16x64_i8 v[84:87], v[158:161], v[198:201], v[84:87]
	v_mfma_i32_16x16x64_i8 v[76:79], v[144:147], v[206:209], v[76:79]
	v_mfma_i32_16x16x64_i8 v[68:71], v[158:161], v[206:209], v[68:71]
	v_mfma_i32_16x16x64_i8 v[124:127], v[148:151], v[186:189], v[124:127]
	v_mfma_i32_16x16x64_i8 v[116:119], v[162:165], v[186:189], v[116:119]
	v_mfma_i32_16x16x64_i8 v[108:111], v[148:151], v[194:197], v[108:111]
	v_mfma_i32_16x16x64_i8 v[100:103], v[162:165], v[194:197], v[100:103]
	v_mfma_i32_16x16x64_i8 v[92:95], v[148:151], v[202:205], v[92:95]
	v_mfma_i32_16x16x64_i8 v[84:87], v[162:165], v[202:205], v[84:87]
	v_mfma_i32_16x16x64_i8 v[76:79], v[148:151], v[210:213], v[76:79]
	v_mfma_i32_16x16x64_i8 v[68:71], v[162:165], v[210:213], v[68:71]
	v_mfma_i32_16x16x64_i8 v[120:123], v[166:169], v[182:185], v[120:123]
	v_mfma_i32_16x16x64_i8 v[112:115], v[174:177], v[182:185], v[112:115]
	v_mfma_i32_16x16x64_i8 v[104:107], v[166:169], v[190:193], v[104:107]
	v_mfma_i32_16x16x64_i8 v[96:99], v[174:177], v[190:193], v[96:99]
	v_mfma_i32_16x16x64_i8 v[88:91], v[166:169], v[198:201], v[88:91]
	v_mfma_i32_16x16x64_i8 v[80:83], v[174:177], v[198:201], v[80:83]
	v_mfma_i32_16x16x64_i8 v[72:75], v[166:169], v[206:209], v[72:75]
	v_mfma_i32_16x16x64_i8 v[64:67], v[174:177], v[206:209], v[64:67]
	v_mfma_i32_16x16x64_i8 v[120:123], v[170:173], v[186:189], v[120:123]
	v_mfma_i32_16x16x64_i8 v[112:115], v[178:181], v[186:189], v[112:115]
	v_mfma_i32_16x16x64_i8 v[104:107], v[170:173], v[194:197], v[104:107]
	v_mfma_i32_16x16x64_i8 v[96:99], v[178:181], v[194:197], v[96:99]
	v_mfma_i32_16x16x64_i8 v[88:91], v[170:173], v[202:205], v[88:91]
	v_mfma_i32_16x16x64_i8 v[80:83], v[178:181], v[202:205], v[80:83]
	v_mfma_i32_16x16x64_i8 v[72:75], v[170:173], v[210:213], v[72:75]
	v_mfma_i32_16x16x64_i8 v[64:67], v[178:181], v[210:213], v[64:67]
	s_barrier
	s_setprio 0
	s_add_i32 s53, s44, s2
	s_mov_b32 m0, s53
	ds_read_b128 v[182:185], v157 offset:16384
	ds_read_b128 v[186:189], v157 offset:17408
	ds_read_b128 v[190:193], v157 offset:18432
	ds_read_b128 v[194:197], v157 offset:19456
	ds_read_b128 v[198:201], v157 offset:20480
	ds_read_b128 v[202:205], v157 offset:21504
	ds_read_b128 v[206:209], v157 offset:22528
	ds_read_b128 v[210:213], v157 offset:23552
	global_load_lds_dwordx4 v132, s[36:37]
	s_add_i32 m0, s53, 0x2000
	s_add_u32 s54, s36, 0x80000
	s_mov_b64 s[98:99], s[36:37]
	s_addc_u32 s55, s37, 0
	s_add_i32 s53, s45, s2
	global_load_lds_dwordx4 v128, s[98:99]
	s_mov_b32 m0, s53
	s_mov_b64 s[100:101], s[38:39]
	global_load_lds_dwordx4 v132, s[54:55]
	s_add_i32 m0, s53, 0x2000
	s_nop 0
	global_load_lds_dwordx4 v128, s[54:55]
	s_mov_b64 s[100:101], s[38:39]
	s_mov_b32 m0, s17
	s_nop 0
	global_load_lds_dwordx4 v134, s[100:101]
	s_mov_b32 m0, s29
	s_nop 0
	global_load_lds_dwordx4 v130, s[100:101]
	s_waitcnt vmcnt(8)
	s_waitcnt lgkmcnt(0)
	s_setprio 1
	s_barrier
	v_mfma_i32_16x16x64_i8 v[60:63], v[144:147], v[182:185], v[60:63]
	v_mfma_i32_16x16x64_i8 v[52:55], v[158:161], v[182:185], v[52:55]
	v_mfma_i32_16x16x64_i8 v[44:47], v[144:147], v[190:193], v[44:47]
	v_mfma_i32_16x16x64_i8 v[36:39], v[158:161], v[190:193], v[36:39]
	v_mfma_i32_16x16x64_i8 v[28:31], v[144:147], v[198:201], v[28:31]
	v_mfma_i32_16x16x64_i8 v[20:23], v[158:161], v[198:201], v[20:23]
	v_mfma_i32_16x16x64_i8 v[12:15], v[144:147], v[206:209], v[12:15]
	v_mfma_i32_16x16x64_i8 v[4:7], v[158:161], v[206:209], v[4:7]
	v_mfma_i32_16x16x64_i8 v[60:63], v[148:151], v[186:189], v[60:63]
	v_mfma_i32_16x16x64_i8 v[52:55], v[162:165], v[186:189], v[52:55]
	v_mfma_i32_16x16x64_i8 v[44:47], v[148:151], v[194:197], v[44:47]
	v_mfma_i32_16x16x64_i8 v[36:39], v[162:165], v[194:197], v[36:39]
	v_mfma_i32_16x16x64_i8 v[28:31], v[148:151], v[202:205], v[28:31]
	v_mfma_i32_16x16x64_i8 v[20:23], v[162:165], v[202:205], v[20:23]
	v_mfma_i32_16x16x64_i8 v[12:15], v[148:151], v[210:213], v[12:15]
	v_mfma_i32_16x16x64_i8 v[4:7], v[162:165], v[210:213], v[4:7]
	v_mfma_i32_16x16x64_i8 v[56:59], v[166:169], v[182:185], v[56:59]
	v_mfma_i32_16x16x64_i8 v[48:51], v[174:177], v[182:185], v[48:51]
	v_mfma_i32_16x16x64_i8 v[40:43], v[166:169], v[190:193], v[40:43]
	v_mfma_i32_16x16x64_i8 v[32:35], v[174:177], v[190:193], v[32:35]
	v_mfma_i32_16x16x64_i8 v[24:27], v[166:169], v[198:201], v[24:27]
	v_mfma_i32_16x16x64_i8 v[16:19], v[174:177], v[198:201], v[16:19]
	v_mfma_i32_16x16x64_i8 v[8:11], v[166:169], v[206:209], v[8:11]
	v_mfma_i32_16x16x64_i8 v[0:3], v[174:177], v[206:209], v[0:3]
	v_mfma_i32_16x16x64_i8 v[56:59], v[170:173], v[186:189], v[56:59]
	v_mfma_i32_16x16x64_i8 v[48:51], v[178:181], v[186:189], v[48:51]
	v_mfma_i32_16x16x64_i8 v[40:43], v[170:173], v[194:197], v[40:43]
	v_mfma_i32_16x16x64_i8 v[32:35], v[178:181], v[194:197], v[32:35]
	v_mfma_i32_16x16x64_i8 v[24:27], v[170:173], v[202:205], v[24:27]
	v_mfma_i32_16x16x64_i8 v[16:19], v[178:181], v[202:205], v[16:19]
	v_mfma_i32_16x16x64_i8 v[8:11], v[170:173], v[210:213], v[8:11]
	v_mfma_i32_16x16x64_i8 v[0:3], v[178:181], v[210:213], v[0:3]
	s_barrier
	s_setprio 0
	s_add_i32 s53, 0, 0x18000
	s_add_i32 s54, 0, 0x1c000
	v_add_u32_e32 v162, s53, v153
	v_add_u32_e32 v178, s54, v153
	ds_read_b128 v[144:147], v162
	ds_read_b128 v[148:151], v162 offset:1024
	ds_read_b128 v[158:161], v162 offset:2048
	ds_read_b128 v[162:165], v162 offset:3072
	ds_read_b128 v[166:169], v178
	ds_read_b128 v[170:173], v178 offset:1024
	ds_read_b128 v[174:177], v178 offset:2048
	ds_read_b128 v[178:181], v178 offset:3072
	s_add_u32 s38, s38, 0x80000
	s_addc_u32 s39, s39, 0
	s_mov_b32 m0, s33
	ds_read_b128 v[182:185], v157 offset:32768
	ds_read_b128 v[186:189], v157 offset:33792
	ds_read_b128 v[190:193], v157 offset:34816
	ds_read_b128 v[194:197], v157 offset:35840
	ds_read_b128 v[198:201], v157 offset:36864
	ds_read_b128 v[202:205], v157 offset:37888
	ds_read_b128 v[206:209], v157 offset:38912
	ds_read_b128 v[210:213], v157 offset:39936
	global_load_lds_dwordx4 v134, s[38:39]
	s_mov_b32 m0, s35
	s_nop 0
	global_load_lds_dwordx4 v130, s[38:39]
	s_waitcnt vmcnt(8)
	s_waitcnt lgkmcnt(0)
	s_setprio 1
	s_barrier
	v_mfma_i32_16x16x64_i8 v[124:127], v[144:147], v[182:185], v[124:127]
	v_mfma_i32_16x16x64_i8 v[116:119], v[158:161], v[182:185], v[116:119]
	v_mfma_i32_16x16x64_i8 v[108:111], v[144:147], v[190:193], v[108:111]
	v_mfma_i32_16x16x64_i8 v[100:103], v[158:161], v[190:193], v[100:103]
	v_mfma_i32_16x16x64_i8 v[92:95], v[144:147], v[198:201], v[92:95]
	v_mfma_i32_16x16x64_i8 v[84:87], v[158:161], v[198:201], v[84:87]
	v_mfma_i32_16x16x64_i8 v[76:79], v[144:147], v[206:209], v[76:79]
	v_mfma_i32_16x16x64_i8 v[68:71], v[158:161], v[206:209], v[68:71]
	v_mfma_i32_16x16x64_i8 v[124:127], v[148:151], v[186:189], v[124:127]
	v_mfma_i32_16x16x64_i8 v[116:119], v[162:165], v[186:189], v[116:119]
	v_mfma_i32_16x16x64_i8 v[108:111], v[148:151], v[194:197], v[108:111]
	v_mfma_i32_16x16x64_i8 v[100:103], v[162:165], v[194:197], v[100:103]
	v_mfma_i32_16x16x64_i8 v[92:95], v[148:151], v[202:205], v[92:95]
	v_mfma_i32_16x16x64_i8 v[84:87], v[162:165], v[202:205], v[84:87]
	v_mfma_i32_16x16x64_i8 v[76:79], v[148:151], v[210:213], v[76:79]
	v_mfma_i32_16x16x64_i8 v[68:71], v[162:165], v[210:213], v[68:71]
	v_mfma_i32_16x16x64_i8 v[120:123], v[166:169], v[182:185], v[120:123]
	v_mfma_i32_16x16x64_i8 v[112:115], v[174:177], v[182:185], v[112:115]
	v_mfma_i32_16x16x64_i8 v[104:107], v[166:169], v[190:193], v[104:107]
	v_mfma_i32_16x16x64_i8 v[96:99], v[174:177], v[190:193], v[96:99]
	v_mfma_i32_16x16x64_i8 v[88:91], v[166:169], v[198:201], v[88:91]
	v_mfma_i32_16x16x64_i8 v[80:83], v[174:177], v[198:201], v[80:83]
	v_mfma_i32_16x16x64_i8 v[72:75], v[166:169], v[206:209], v[72:75]
	v_mfma_i32_16x16x64_i8 v[64:67], v[174:177], v[206:209], v[64:67]
	v_mfma_i32_16x16x64_i8 v[120:123], v[170:173], v[186:189], v[120:123]
	v_mfma_i32_16x16x64_i8 v[112:115], v[178:181], v[186:189], v[112:115]
	v_mfma_i32_16x16x64_i8 v[104:107], v[170:173], v[194:197], v[104:107]
	v_mfma_i32_16x16x64_i8 v[96:99], v[178:181], v[194:197], v[96:99]
	v_mfma_i32_16x16x64_i8 v[88:91], v[170:173], v[202:205], v[88:91]
	v_mfma_i32_16x16x64_i8 v[80:83], v[178:181], v[202:205], v[80:83]
	v_mfma_i32_16x16x64_i8 v[72:75], v[170:173], v[210:213], v[72:75]
	v_mfma_i32_16x16x64_i8 v[64:67], v[178:181], v[210:213], v[64:67]
	s_barrier
	s_setprio 0
	s_add_i32 s38, s53, s2
	s_add_i32 m0, s38, -128
	ds_read_b128 v[182:185], v157 offset:49152
	ds_read_b128 v[186:189], v157 offset:50176
	ds_read_b128 v[190:193], v157 offset:51200
	ds_read_b128 v[194:197], v157 offset:52224
	ds_read_b128 v[198:201], v157 offset:53248
	ds_read_b128 v[202:205], v157 offset:54272
	ds_read_b128 v[206:209], v157 offset:55296
	ds_read_b128 v[210:213], v157 offset:56320
	global_load_lds_dwordx4 v132, s[36:37] offset:128
	s_add_i32 m0, s38, 8064
	s_add_u32 s36, s36, 0x80080
	s_addc_u32 s37, s37, 0
	s_add_i32 s38, s54, s2
	global_load_lds_dwordx4 v128, s[98:99] offset:128
	s_mov_b32 m0, s38
	s_nop 0
	global_load_lds_dwordx4 v132, s[36:37]
	s_add_i32 m0, s38, 0x2000
	s_nop 0
	global_load_lds_dwordx4 v128, s[36:37]
	s_add_i32 m0, s42, -128
	s_nop 0
	global_load_lds_dwordx4 v134, s[100:101] offset:128
	s_add_i32 m0, s43, -128
	s_nop 0
	global_load_lds_dwordx4 v130, s[100:101] offset:128
	s_waitcnt vmcnt(8)
	s_waitcnt lgkmcnt(0)
	s_setprio 1
	s_barrier
	v_mfma_i32_16x16x64_i8 v[60:63], v[144:147], v[182:185], v[60:63]
	v_mfma_i32_16x16x64_i8 v[52:55], v[158:161], v[182:185], v[52:55]
	v_mfma_i32_16x16x64_i8 v[44:47], v[144:147], v[190:193], v[44:47]
	v_mfma_i32_16x16x64_i8 v[36:39], v[158:161], v[190:193], v[36:39]
	v_mfma_i32_16x16x64_i8 v[28:31], v[144:147], v[198:201], v[28:31]
	v_mfma_i32_16x16x64_i8 v[20:23], v[158:161], v[198:201], v[20:23]
	v_mfma_i32_16x16x64_i8 v[12:15], v[144:147], v[206:209], v[12:15]
	v_mfma_i32_16x16x64_i8 v[4:7], v[158:161], v[206:209], v[4:7]
	v_mfma_i32_16x16x64_i8 v[60:63], v[148:151], v[186:189], v[60:63]
	v_mfma_i32_16x16x64_i8 v[52:55], v[162:165], v[186:189], v[52:55]
	v_mfma_i32_16x16x64_i8 v[44:47], v[148:151], v[194:197], v[44:47]
	v_mfma_i32_16x16x64_i8 v[36:39], v[162:165], v[194:197], v[36:39]
	v_mfma_i32_16x16x64_i8 v[28:31], v[148:151], v[202:205], v[28:31]
	v_mfma_i32_16x16x64_i8 v[20:23], v[162:165], v[202:205], v[20:23]
	v_mfma_i32_16x16x64_i8 v[12:15], v[148:151], v[210:213], v[12:15]
	v_mfma_i32_16x16x64_i8 v[4:7], v[162:165], v[210:213], v[4:7]
	v_mfma_i32_16x16x64_i8 v[56:59], v[166:169], v[182:185], v[56:59]
	v_mfma_i32_16x16x64_i8 v[48:51], v[174:177], v[182:185], v[48:51]
	v_mfma_i32_16x16x64_i8 v[40:43], v[166:169], v[190:193], v[40:43]
	v_mfma_i32_16x16x64_i8 v[32:35], v[174:177], v[190:193], v[32:35]
	v_mfma_i32_16x16x64_i8 v[24:27], v[166:169], v[198:201], v[24:27]
	v_mfma_i32_16x16x64_i8 v[16:19], v[174:177], v[198:201], v[16:19]
	v_mfma_i32_16x16x64_i8 v[8:11], v[166:169], v[206:209], v[8:11]
	v_mfma_i32_16x16x64_i8 v[0:3], v[174:177], v[206:209], v[0:3]
	v_mfma_i32_16x16x64_i8 v[56:59], v[170:173], v[186:189], v[56:59]
	v_mfma_i32_16x16x64_i8 v[48:51], v[178:181], v[186:189], v[48:51]
	v_mfma_i32_16x16x64_i8 v[40:43], v[170:173], v[194:197], v[40:43]
	v_mfma_i32_16x16x64_i8 v[32:35], v[178:181], v[194:197], v[32:35]
	v_mfma_i32_16x16x64_i8 v[24:27], v[170:173], v[202:205], v[24:27]
	v_mfma_i32_16x16x64_i8 v[16:19], v[178:181], v[202:205], v[16:19]
	v_mfma_i32_16x16x64_i8 v[8:11], v[170:173], v[210:213], v[8:11]
	v_mfma_i32_16x16x64_i8 v[0:3], v[178:181], v[210:213], v[0:3]
	s_barrier
	s_setprio 0
	s_add_i32 s52, s52, 2
	s_add_u32 s30, s30, 0x100
	s_addc_u32 s31, s31, 0
	s_add_u32 s50, s50, 0x100
	s_addc_u32 s51, s51, 0
	s_cmp_gt_u32 s52, 29
	s_cbranch_scc0 .LBB0_773
	s_and_b64 vcc, exec, s[14:15]
	s_cbranch_vccz .LBB0_776
	s_barrier

.LBB0_858:
	ds_read_b128 v[152:155], v149
	ds_read_b128 v[156:159], v149 offset:1024
	ds_read_b128 v[160:163], v149 offset:2048
	ds_read_b128 v[164:167], v149 offset:3072
	ds_read_b128 v[168:171], v150
	ds_read_b128 v[172:175], v150 offset:1024
	ds_read_b128 v[176:179], v150 offset:2048
	ds_read_b128 v[180:183], v150 offset:3072
	s_add_u32 s26, s24, 0x100
	s_addc_u32 s27, s25, 0
	s_cmpk_eq_i32 s54, 0xa8
	s_cselect_b32 s31, s5, s27
	s_cselect_b32 s30, s4, s26
	s_cselect_b32 s29, s23, s53
	s_cselect_b32 s28, s22, s52
	s_add_i32 m0, s33, 0xc000
	ds_read_b128 v[184:187], v151
	ds_read_b128 v[188:191], v151 offset:1024
	ds_read_b128 v[192:195], v151 offset:2048
	ds_read_b128 v[196:199], v151 offset:3072
	ds_read_b128 v[200:203], v151 offset:4096
	ds_read_b128 v[204:207], v151 offset:5120
	ds_read_b128 v[208:211], v151 offset:6144
	ds_read_b128 v[212:215], v151 offset:7168
	global_load_lds_dwordx4 v136, s[24:25]
	s_add_i32 m0, s33, 0xe000
	s_nop 0
	global_load_lds_dwordx4 v138, s[24:25]
	s_waitcnt vmcnt(8)
	s_waitcnt lgkmcnt(0)
	s_setprio 1
	s_barrier
	v_mfma_f32_16x16x32_bf16 v[124:127], v[152:155], v[184:187], v[124:127]
	v_mfma_f32_16x16x32_bf16 v[120:123], v[160:163], v[184:187], v[120:123]
	v_mfma_f32_16x16x32_bf16 v[116:119], v[152:155], v[192:195], v[116:119]
	v_mfma_f32_16x16x32_bf16 v[108:111], v[160:163], v[192:195], v[108:111]
	v_mfma_f32_16x16x32_bf16 v[100:103], v[152:155], v[200:203], v[100:103]
	v_mfma_f32_16x16x32_bf16 v[92:95], v[160:163], v[200:203], v[92:95]
	v_mfma_f32_16x16x32_bf16 v[84:87], v[152:155], v[208:211], v[84:87]
	v_mfma_f32_16x16x32_bf16 v[76:79], v[160:163], v[208:211], v[76:79]
	v_mfma_f32_16x16x32_bf16 v[124:127], v[156:159], v[188:191], v[124:127]
	v_mfma_f32_16x16x32_bf16 v[120:123], v[164:167], v[188:191], v[120:123]
	v_mfma_f32_16x16x32_bf16 v[116:119], v[156:159], v[196:199], v[116:119]
	v_mfma_f32_16x16x32_bf16 v[108:111], v[164:167], v[196:199], v[108:111]
	v_mfma_f32_16x16x32_bf16 v[100:103], v[156:159], v[204:207], v[100:103]
	v_mfma_f32_16x16x32_bf16 v[92:95], v[164:167], v[204:207], v[92:95]
	v_mfma_f32_16x16x32_bf16 v[84:87], v[156:159], v[212:215], v[84:87]
	v_mfma_f32_16x16x32_bf16 v[76:79], v[164:167], v[212:215], v[76:79]
	v_mfma_f32_16x16x32_bf16 v[112:115], v[168:171], v[184:187], v[112:115]
	v_mfma_f32_16x16x32_bf16 v[104:107], v[176:179], v[184:187], v[104:107]
	v_mfma_f32_16x16x32_bf16 v[96:99], v[168:171], v[192:195], v[96:99]
	v_mfma_f32_16x16x32_bf16 v[88:91], v[176:179], v[192:195], v[88:91]
	v_mfma_f32_16x16x32_bf16 v[80:83], v[168:171], v[200:203], v[80:83]
	v_mfma_f32_16x16x32_bf16 v[72:75], v[176:179], v[200:203], v[72:75]
	v_mfma_f32_16x16x32_bf16 v[68:71], v[168:171], v[208:211], v[68:71]
	v_mfma_f32_16x16x32_bf16 v[64:67], v[176:179], v[208:211], v[64:67]
	v_mfma_f32_16x16x32_bf16 v[112:115], v[172:175], v[188:191], v[112:115]
	v_mfma_f32_16x16x32_bf16 v[104:107], v[180:183], v[188:191], v[104:107]
	v_mfma_f32_16x16x32_bf16 v[96:99], v[172:175], v[196:199], v[96:99]
	v_mfma_f32_16x16x32_bf16 v[88:91], v[180:183], v[196:199], v[88:91]
	v_mfma_f32_16x16x32_bf16 v[80:83], v[172:175], v[204:207], v[80:83]
	v_mfma_f32_16x16x32_bf16 v[72:75], v[180:183], v[204:207], v[72:75]
	v_mfma_f32_16x16x32_bf16 v[68:71], v[172:175], v[212:215], v[68:71]
	v_mfma_f32_16x16x32_bf16 v[64:67], v[180:183], v[212:215], v[64:67]
	s_barrier
	s_setprio 0
	s_add_i32 s24, s42, s2
	s_mov_b32 m0, s24
	ds_read_b128 v[184:187], v151 offset:16384
	ds_read_b128 v[188:191], v151 offset:17408
	ds_read_b128 v[192:195], v151 offset:18432
	ds_read_b128 v[196:199], v151 offset:19456
	ds_read_b128 v[200:203], v151 offset:20480
	ds_read_b128 v[204:207], v151 offset:21504
	ds_read_b128 v[208:211], v151 offset:22528
	ds_read_b128 v[212:215], v151 offset:23552
	global_load_lds_dwordx4 v132, s[28:29]
	s_add_i32 m0, s24, 0x2000
	s_add_u32 s24, s28, 0x2b0000
	s_mov_b64 s[98:99], s[28:29]
	s_addc_u32 s25, s29, 0
	s_add_i32 s55, s43, s2
	global_load_lds_dwordx4 v128, s[98:99]
	s_mov_b32 m0, s55
	s_nop 0
	global_load_lds_dwordx4 v132, s[24:25]
	s_add_i32 m0, s55, 0x2000
	s_nop 0
	global_load_lds_dwordx4 v128, s[24:25]
	s_mov_b32 m0, s33
	s_nop 0
	global_load_lds_dwordx4 v134, s[30:31]
	s_mov_b32 m0, s35
	s_nop 0
	global_load_lds_dwordx4 v130, s[30:31]
	s_waitcnt vmcnt(8)
	s_waitcnt lgkmcnt(0)
	s_setprio 1
	s_barrier
	v_mfma_f32_16x16x32_bf16 v[60:63], v[152:155], v[184:187], v[60:63]
	v_mfma_f32_16x16x32_bf16 v[56:59], v[160:163], v[184:187], v[56:59]
	v_mfma_f32_16x16x32_bf16 v[52:55], v[152:155], v[192:195], v[52:55]
	v_mfma_f32_16x16x32_bf16 v[44:47], v[160:163], v[192:195], v[44:47]
	v_mfma_f32_16x16x32_bf16 v[36:39], v[152:155], v[200:203], v[36:39]
	v_mfma_f32_16x16x32_bf16 v[28:31], v[160:163], v[200:203], v[28:31]
	v_mfma_f32_16x16x32_bf16 v[20:23], v[152:155], v[208:211], v[20:23]
	v_mfma_f32_16x16x32_bf16 v[12:15], v[160:163], v[208:211], v[12:15]
	v_mfma_f32_16x16x32_bf16 v[60:63], v[156:159], v[188:191], v[60:63]
	v_mfma_f32_16x16x32_bf16 v[56:59], v[164:167], v[188:191], v[56:59]
	v_mfma_f32_16x16x32_bf16 v[52:55], v[156:159], v[196:199], v[52:55]
	v_mfma_f32_16x16x32_bf16 v[44:47], v[164:167], v[196:199], v[44:47]
	v_mfma_f32_16x16x32_bf16 v[36:39], v[156:159], v[204:207], v[36:39]
	v_mfma_f32_16x16x32_bf16 v[28:31], v[164:167], v[204:207], v[28:31]
	v_mfma_f32_16x16x32_bf16 v[20:23], v[156:159], v[212:215], v[20:23]
	v_mfma_f32_16x16x32_bf16 v[12:15], v[164:167], v[212:215], v[12:15]
	v_mfma_f32_16x16x32_bf16 v[48:51], v[168:171], v[184:187], v[48:51]
	v_mfma_f32_16x16x32_bf16 v[40:43], v[176:179], v[184:187], v[40:43]
	v_mfma_f32_16x16x32_bf16 v[32:35], v[168:171], v[192:195], v[32:35]
	v_mfma_f32_16x16x32_bf16 v[24:27], v[176:179], v[192:195], v[24:27]
	v_mfma_f32_16x16x32_bf16 v[16:19], v[168:171], v[200:203], v[16:19]
	v_mfma_f32_16x16x32_bf16 v[8:11], v[176:179], v[200:203], v[8:11]
	v_mfma_f32_16x16x32_bf16 v[4:7], v[168:171], v[208:211], v[4:7]
	v_mfma_f32_16x16x32_bf16 v[0:3], v[176:179], v[208:211], v[0:3]
	v_mfma_f32_16x16x32_bf16 v[48:51], v[172:175], v[188:191], v[48:51]
	v_mfma_f32_16x16x32_bf16 v[40:43], v[180:183], v[188:191], v[40:43]
	v_mfma_f32_16x16x32_bf16 v[32:35], v[172:175], v[196:199], v[32:35]
	v_mfma_f32_16x16x32_bf16 v[24:27], v[180:183], v[196:199], v[24:27]
	v_mfma_f32_16x16x32_bf16 v[16:19], v[172:175], v[204:207], v[16:19]
	v_mfma_f32_16x16x32_bf16 v[8:11], v[180:183], v[204:207], v[8:11]
	v_mfma_f32_16x16x32_bf16 v[4:7], v[172:175], v[212:215], v[4:7]
	v_mfma_f32_16x16x32_bf16 v[0:3], v[180:183], v[212:215], v[0:3]
	s_barrier
	s_setprio 0
	s_add_i32 s55, 0, 0x18000
	s_add_i32 s58, 0, 0x1c000
	v_add_u32_e32 v164, s55, v147
	v_add_u32_e32 v180, s58, v147
	ds_read_b128 v[152:155], v164
	ds_read_b128 v[156:159], v164 offset:1024
	ds_read_b128 v[160:163], v164 offset:2048
	ds_read_b128 v[164:167], v164 offset:3072
	ds_read_b128 v[168:171], v180
	ds_read_b128 v[172:175], v180 offset:1024
	ds_read_b128 v[176:179], v180 offset:2048
	ds_read_b128 v[180:183], v180 offset:3072
	s_add_u32 s24, s30, 0x2b0000
	s_addc_u32 s25, s31, 0
	s_mov_b32 m0, s36
	ds_read_b128 v[184:187], v151 offset:32768
	ds_read_b128 v[188:191], v151 offset:33792
	ds_read_b128 v[192:195], v151 offset:34816
	ds_read_b128 v[196:199], v151 offset:35840
	ds_read_b128 v[200:203], v151 offset:36864
	ds_read_b128 v[204:207], v151 offset:37888
	ds_read_b128 v[208:211], v151 offset:38912
	ds_read_b128 v[212:215], v151 offset:39936
	global_load_lds_dwordx4 v134, s[24:25]
	s_mov_b32 m0, s37
	s_nop 0
	global_load_lds_dwordx4 v130, s[24:25]
	s_waitcnt vmcnt(8)
	s_waitcnt lgkmcnt(0)
	s_setprio 1
	s_barrier
	v_mfma_f32_16x16x32_bf16 v[124:127], v[152:155], v[184:187], v[124:127]
	v_mfma_f32_16x16x32_bf16 v[120:123], v[160:163], v[184:187], v[120:123]
	v_mfma_f32_16x16x32_bf16 v[116:119], v[152:155], v[192:195], v[116:119]
	v_mfma_f32_16x16x32_bf16 v[108:111], v[160:163], v[192:195], v[108:111]
	v_mfma_f32_16x16x32_bf16 v[100:103], v[152:155], v[200:203], v[100:103]
	v_mfma_f32_16x16x32_bf16 v[92:95], v[160:163], v[200:203], v[92:95]
	v_mfma_f32_16x16x32_bf16 v[84:87], v[152:155], v[208:211], v[84:87]
	v_mfma_f32_16x16x32_bf16 v[76:79], v[160:163], v[208:211], v[76:79]
	v_mfma_f32_16x16x32_bf16 v[124:127], v[156:159], v[188:191], v[124:127]
	v_mfma_f32_16x16x32_bf16 v[120:123], v[164:167], v[188:191], v[120:123]
	v_mfma_f32_16x16x32_bf16 v[116:119], v[156:159], v[196:199], v[116:119]
	v_mfma_f32_16x16x32_bf16 v[108:111], v[164:167], v[196:199], v[108:111]
	v_mfma_f32_16x16x32_bf16 v[100:103], v[156:159], v[204:207], v[100:103]
	v_mfma_f32_16x16x32_bf16 v[92:95], v[164:167], v[204:207], v[92:95]
	v_mfma_f32_16x16x32_bf16 v[84:87], v[156:159], v[212:215], v[84:87]
	v_mfma_f32_16x16x32_bf16 v[76:79], v[164:167], v[212:215], v[76:79]
	v_mfma_f32_16x16x32_bf16 v[112:115], v[168:171], v[184:187], v[112:115]
	v_mfma_f32_16x16x32_bf16 v[104:107], v[176:179], v[184:187], v[104:107]
	v_mfma_f32_16x16x32_bf16 v[96:99], v[168:171], v[192:195], v[96:99]
	v_mfma_f32_16x16x32_bf16 v[88:91], v[176:179], v[192:195], v[88:91]
	v_mfma_f32_16x16x32_bf16 v[80:83], v[168:171], v[200:203], v[80:83]
	v_mfma_f32_16x16x32_bf16 v[72:75], v[176:179], v[200:203], v[72:75]
	v_mfma_f32_16x16x32_bf16 v[68:71], v[168:171], v[208:211], v[68:71]
	v_mfma_f32_16x16x32_bf16 v[64:67], v[176:179], v[208:211], v[64:67]
	v_mfma_f32_16x16x32_bf16 v[112:115], v[172:175], v[188:191], v[112:115]
	v_mfma_f32_16x16x32_bf16 v[104:107], v[180:183], v[188:191], v[104:107]
	v_mfma_f32_16x16x32_bf16 v[96:99], v[172:175], v[196:199], v[96:99]
	v_mfma_f32_16x16x32_bf16 v[88:91], v[180:183], v[196:199], v[88:91]
	v_mfma_f32_16x16x32_bf16 v[80:83], v[172:175], v[204:207], v[80:83]
	v_mfma_f32_16x16x32_bf16 v[72:75], v[180:183], v[204:207], v[72:75]
	v_mfma_f32_16x16x32_bf16 v[68:71], v[172:175], v[212:215], v[68:71]
	v_mfma_f32_16x16x32_bf16 v[64:67], v[180:183], v[212:215], v[64:67]
	s_barrier
	s_setprio 0
	s_add_i32 s24, s55, s2
	s_add_i32 m0, s24, -128
	ds_read_b128 v[184:187], v151 offset:49152
	ds_read_b128 v[188:191], v151 offset:50176
	ds_read_b128 v[192:195], v151 offset:51200
	ds_read_b128 v[196:199], v151 offset:52224
	ds_read_b128 v[200:203], v151 offset:53248
	ds_read_b128 v[204:207], v151 offset:54272
	ds_read_b128 v[208:211], v151 offset:55296
	ds_read_b128 v[212:215], v151 offset:56320
	global_load_lds_dwordx4 v132, s[28:29] offset:128
	s_add_i32 m0, s24, 8064
	s_add_u32 s24, s28, 0x2b0080
	s_addc_u32 s25, s29, 0
	s_add_i32 s28, s58, s2
	global_load_lds_dwordx4 v128, s[98:99] offset:128
	s_mov_b32 m0, s28
	s_nop 0
	global_load_lds_dwordx4 v132, s[24:25]
	s_add_i32 m0, s28, 0x2000
	s_nop 0
	global_load_lds_dwordx4 v128, s[24:25]
	s_add_i32 m0, s40, -128
	s_nop 0
	global_load_lds_dwordx4 v134, s[30:31] offset:128
	s_add_i32 m0, s41, -128
	s_nop 0
	global_load_lds_dwordx4 v130, s[30:31] offset:128
	s_waitcnt vmcnt(8)
	s_waitcnt lgkmcnt(0)
	s_setprio 1
	s_barrier
	v_mfma_f32_16x16x32_bf16 v[60:63], v[152:155], v[184:187], v[60:63]
	v_mfma_f32_16x16x32_bf16 v[56:59], v[160:163], v[184:187], v[56:59]
	v_mfma_f32_16x16x32_bf16 v[52:55], v[152:155], v[192:195], v[52:55]
	v_mfma_f32_16x16x32_bf16 v[44:47], v[160:163], v[192:195], v[44:47]
	v_mfma_f32_16x16x32_bf16 v[36:39], v[152:155], v[200:203], v[36:39]
	v_mfma_f32_16x16x32_bf16 v[28:31], v[160:163], v[200:203], v[28:31]
	v_mfma_f32_16x16x32_bf16 v[20:23], v[152:155], v[208:211], v[20:23]
	v_mfma_f32_16x16x32_bf16 v[12:15], v[160:163], v[208:211], v[12:15]
	v_mfma_f32_16x16x32_bf16 v[60:63], v[156:159], v[188:191], v[60:63]
	v_mfma_f32_16x16x32_bf16 v[56:59], v[164:167], v[188:191], v[56:59]
	v_mfma_f32_16x16x32_bf16 v[52:55], v[156:159], v[196:199], v[52:55]
	v_mfma_f32_16x16x32_bf16 v[44:47], v[164:167], v[196:199], v[44:47]
	v_mfma_f32_16x16x32_bf16 v[36:39], v[156:159], v[204:207], v[36:39]
	v_mfma_f32_16x16x32_bf16 v[28:31], v[164:167], v[204:207], v[28:31]
	v_mfma_f32_16x16x32_bf16 v[20:23], v[156:159], v[212:215], v[20:23]
	v_mfma_f32_16x16x32_bf16 v[12:15], v[164:167], v[212:215], v[12:15]
	v_mfma_f32_16x16x32_bf16 v[48:51], v[168:171], v[184:187], v[48:51]
	v_mfma_f32_16x16x32_bf16 v[40:43], v[176:179], v[184:187], v[40:43]
	v_mfma_f32_16x16x32_bf16 v[32:35], v[168:171], v[192:195], v[32:35]
	v_mfma_f32_16x16x32_bf16 v[24:27], v[176:179], v[192:195], v[24:27]
	v_mfma_f32_16x16x32_bf16 v[16:19], v[168:171], v[200:203], v[16:19]
	v_mfma_f32_16x16x32_bf16 v[8:11], v[176:179], v[200:203], v[8:11]
	v_mfma_f32_16x16x32_bf16 v[4:7], v[168:171], v[208:211], v[4:7]
	v_mfma_f32_16x16x32_bf16 v[0:3], v[176:179], v[208:211], v[0:3]
	v_mfma_f32_16x16x32_bf16 v[48:51], v[172:175], v[188:191], v[48:51]
	v_mfma_f32_16x16x32_bf16 v[40:43], v[180:183], v[188:191], v[40:43]
	v_mfma_f32_16x16x32_bf16 v[32:35], v[172:175], v[196:199], v[32:35]
	v_mfma_f32_16x16x32_bf16 v[24:27], v[180:183], v[196:199], v[24:27]
	v_mfma_f32_16x16x32_bf16 v[16:19], v[172:175], v[204:207], v[16:19]
	v_mfma_f32_16x16x32_bf16 v[8:11], v[180:183], v[204:207], v[8:11]
	v_mfma_f32_16x16x32_bf16 v[4:7], v[172:175], v[212:215], v[4:7]
	v_mfma_f32_16x16x32_bf16 v[0:3], v[180:183], v[212:215], v[0:3]
	s_barrier
	s_setprio 0
	s_add_i32 s54, s54, 2
	s_add_u32 s52, s52, 0x100
	s_addc_u32 s53, s53, 0
	s_cmpk_gt_u32 s54, 0xa9
	s_mov_b64 s[24:25], s[26:27]
	s_cbranch_scc0 .LBB0_858
	s_and_b64 vcc, exec, s[10:11]
	s_cbranch_vccz .LBB0_861
	s_barrier

	.amdhsa_kernel _Z6mk_fwd4Args
		.amdhsa_group_segment_fixed_size 0
		.amdhsa_private_segment_fixed_size 0
		.amdhsa_kernarg_size 448
		.amdhsa_user_sgpr_count 2
		.amdhsa_user_sgpr_dispatch_ptr 0
		.amdhsa_user_sgpr_queue_ptr 0
		.amdhsa_user_sgpr_kernarg_segment_ptr 1
		.amdhsa_user_sgpr_dispatch_id 0
		.amdhsa_user_sgpr_kernarg_preload_length 0
		.amdhsa_user_sgpr_kernarg_preload_offset 0
		.amdhsa_user_sgpr_private_segment_size 0
		.amdhsa_uses_dynamic_stack 0
		.amdhsa_enable_private_segment 0
		.amdhsa_system_sgpr_workgroup_id_x 1
		.amdhsa_system_sgpr_workgroup_id_y 0
		.amdhsa_system_sgpr_workgroup_id_z 0
		.amdhsa_system_sgpr_workgroup_info 0
		.amdhsa_system_vgpr_workitem_id 0
		.amdhsa_next_free_vgpr 251
		.amdhsa_next_free_sgpr 102
		.amdhsa_accum_offset 252
		.amdhsa_reserve_vcc 1
		.amdhsa_float_round_mode_32 0
		.amdhsa_float_round_mode_16_64 0
		.amdhsa_float_denorm_mode_32 3
		.amdhsa_float_denorm_mode_16_64 3
		.amdhsa_dx10_clamp 1
		.amdhsa_ieee_mode 1
		.amdhsa_fp16_overflow 0
		.amdhsa_tg_split 0
		.amdhsa_exception_fp_ieee_invalid_op 0
		.amdhsa_exception_fp_denorm_src 0
		.amdhsa_exception_fp_ieee_div_zero 0
		.amdhsa_exception_fp_ieee_overflow 0
		.amdhsa_exception_fp_ieee_underflow 0
		.amdhsa_exception_fp_ieee_inexact 0
		.amdhsa_exception_int_div_zero 0
	.end_amdhsa_kernel

amdhsa.kernels:
  - .agpr_count:     0
    .args:
      - .offset:         0
        .size:           192
        .value_kind:     by_value
      - .offset:         192
        .size:           4
        .value_kind:     hidden_block_count_x
      - .offset:         196
        .size:           4
        .value_kind:     hidden_block_count_y
      - .offset:         200
        .size:           4
        .value_kind:     hidden_block_count_z
      - .offset:         204
        .size:           2
        .value_kind:     hidden_group_size_x
      - .offset:         206
        .size:           2
        .value_kind:     hidden_group_size_y
      - .offset:         208
        .size:           2
        .value_kind:     hidden_group_size_z
      - .offset:         210
        .size:           2
        .value_kind:     hidden_remainder_x
      - .offset:         212
        .size:           2
        .value_kind:     hidden_remainder_y
      - .offset:         214
        .size:           2
        .value_kind:     hidden_remainder_z
      - .offset:         232
        .size:           8
        .value_kind:     hidden_global_offset_x
      - .offset:         240
        .size:           8
        .value_kind:     hidden_global_offset_y
      - .offset:         248
        .size:           8
        .value_kind:     hidden_global_offset_z
      - .offset:         256
        .size:           2
        .value_kind:     hidden_grid_dims
      - .offset:         312
        .size:           4
        .value_kind:     hidden_dynamic_lds_size
    .group_segment_fixed_size: 0
    .kernarg_segment_align: 8
    .kernarg_segment_size: 448
    .language:       OpenCL C
    .language_version:
      - 2
      - 0
    .max_flat_workgroup_size: 512
    .name:           _Z6mk_fwd4Args
    .private_segment_fixed_size: 0
    .sgpr_count:     108
    .sgpr_spill_count: 41
    .symbol:         _Z6mk_fwd4Args.kd
    .uniform_work_group_size: 1
    .uses_dynamic_stack: false
    .vgpr_count:     251
    .vgpr_spill_count: 0
    .wavefront_size: 64
